# batch alias-serialized RMW chains: lru pass-1 gate loads hoisted (16 in flight), out-GEMM residual epilogue 64 loads in flight
# speedup vs baseline: 1.0633x; 1.0441x over previous
;     ...
;   for (int kt = 0; kt < nk; ++kt) {
;     asm volatile("s_waitcnt vmcnt(0)" ::: "memory");
;     __builtin_amdgcn_s_barrier();
;     if (kt + 1 < nk) stage(kt + 1, (kt + 1) & 1);
;     else if (chained && nbrow >= 0) {
;       const bfr* na = (nA ? nA : A) + (long)(nbrow + r0) * lda + cg;
;       const bfr* nb = (nBt ? nBt : Bt) + (long)(nbcol + r0) * ldb + cg;
; #pragma unroll
;       for (int i = 0; i < 4; ++i)
;         __builtin_amdgcn_global_load_lds((const unsigned*)(na + i * a32), (unsigned*)(smem + tid * 16 + i * 4096), 16, 0, 0);
; #pragma unroll
;       for (int i = 0; i < NF; ++i)
;         __builtin_amdgcn_global_load_lds((const unsigned*)(nb + i * b32), (unsigned*)(smem + 16384 + tid * 16 + i * 4096), 16, 0, 0);
;     }
;     const unsigned bo = (kt & 1) * 32768;
;     bf16x8 af[2][4], bfg[2][4];
;     if (NF == 4) {
;       asm volatile(
;           "ds_read_b128 %0, %16\n\tds_read_b128 %1, %16 offset:2048\n\tds_read_b128 %2, %16 offset:4096\n\tds_read_b128 %3, %16 offset:6144\n\t"
;           "ds_read_b128 %4, %17\n\tds_read_b128 %5, %17 offset:2048\n\tds_read_b128 %6, %17 offset:4096\n\tds_read_b128 %7, %17 offset:6144\n\t"
;           "ds_read_b128 %8, %18\n\tds_read_b128 %9, %18 offset:2048\n\tds_read_b128 %10, %18 offset:4096\n\tds_read_b128 %11, %18 offset:6144\n\t"
;           "ds_read_b128 %12, %19\n\tds_read_b128 %13, %19 offset:2048\n\tds_read_b128 %14, %19 offset:4096\n\tds_read_b128 %15, %19 offset:6144\n\t"
;           "s_waitcnt lgkmcnt(0)"
;           : "=&v"(af[0][0]), "=&v"(af[0][1]), "=&v"(af[0][2]), "=&v"(af[0][3]), "=&v"(bfg[0][0]), "=&v"(bfg[0][1]), "=&v"(bfg[0][2]), "=&v"(bfg[0][3]),
;             "=&v"(af[1][0]), "=&v"(af[1][1]), "=&v"(af[1][2]), "=&v"(af[1][3]), "=&v"(bfg[1][0]), "=&v"(bfg[1][1]), "=&v"(bfg[1][2]), "=&v"(bfg[1][3])
;           : "v"(arow + sw0 + bo), "v"(brw + sw0 + bo), "v"(arow + sw1 + bo), "v"(brw + sw1 + bo)
;           : "memory");
;     } else {
;       asm volatile(
;           "ds_read_b128 %0, %12\n\tds_read_b128 %1, %12 offset:2048\n\tds_read_b128 %2, %12 offset:4096\n\tds_read_b128 %3, %12 offset:6144\n\t"
;           "ds_read_b128 %4, %13\n\tds_read_b128 %5, %13 offset:2048\n\t"
;           "ds_read_b128 %6, %14\n\tds_read_b128 %7, %14 offset:2048\n\tds_read_b128 %8, %14 offset:4096\n\tds_read_b128 %9, %14 offset:6144\n\t"
.LBB0_231:
	s_add_i32 s5, s4, 0x8000
	s_and_b32 s48, s5, 0x8000
	v_add_u32_e32 v65, s48, v75
	v_lshl_add_u64 v[76:77], v[66:67], 0, s[2:3]
	v_readfirstlane_b32 s48, v65
	v_add_u32_e32 v80, 0x1000, v65
	v_lshl_add_u64 v[78:79], v[76:77], 0, s[50:51]
	s_mov_b32 m0, s48
	v_readfirstlane_b32 s48, v80
	v_add_u32_e32 v80, 0x2000, v65
	s_waitcnt vmcnt(0)
	s_barrier
	global_load_lds_dwordx4 v[78:79], off
	v_lshl_add_u64 v[78:79], v[76:77], 0, s[52:53]
	s_mov_b32 m0, s48
	v_readfirstlane_b32 s48, v80
	global_load_lds_dwordx4 v[78:79], off
	v_lshl_add_u64 v[78:79], v[76:77], 0, s[74:75]
	s_mov_b32 m0, s48
	v_lshl_add_u64 v[76:77], v[76:77], 0, s[76:77]
	global_load_lds_dwordx4 v[78:79], off
	v_add_u32_e32 v78, 0x3000, v65
	v_add_u32_e32 v80, 0x4000, v65
	v_readfirstlane_b32 s48, v78
	s_mov_b32 m0, s48
	s_mov_b64 s[48:49], 0x48480
	global_load_lds_dwordx4 v[76:77], off
	v_lshl_add_u64 v[76:77], v[68:69], 0, s[2:3]
	v_lshl_add_u64 v[78:79], v[76:77], 0, s[48:49]
	v_readfirstlane_b32 s48, v80
	s_mov_b32 m0, s48
	s_mov_b64 s[48:49], 0x58480
	v_add_u32_e32 v80, 0x5000, v65
	global_load_lds_dwordx4 v[78:79], off
	v_lshl_add_u64 v[78:79], v[76:77], 0, s[48:49]
	v_readfirstlane_b32 s48, v80
	s_mov_b32 m0, s48
	s_mov_b64 s[48:49], 0x68480
	v_add_u32_e32 v80, 0x6000, v65
	global_load_lds_dwordx4 v[78:79], off
	v_lshl_add_u64 v[78:79], v[76:77], 0, s[48:49]
	v_readfirstlane_b32 s48, v80
	s_mov_b32 m0, s48
	s_mov_b64 s[48:49], 0x78480
	v_add_u32_e32 v65, 0x7000, v65
	v_lshl_add_u64 v[76:77], v[76:77], 0, s[48:49]
	v_readfirstlane_b32 s48, v65
	global_load_lds_dwordx4 v[78:79], off
	s_mov_b32 m0, s48
	s_and_b32 s4, s4, 0x8000
	global_load_lds_dwordx4 v[76:77], off
	v_add_u32_e32 v65, s4, v71
	v_add_u32_e32 v128, s4, v72
	v_add_u32_e32 v132, s4, v73
	v_add_u32_e32 v133, s4, v74
	ds_read_b128 v[76:79], v65
	ds_read_b128 v[80:83], v65 offset:2048
	ds_read_b128 v[84:87], v65 offset:4096
	ds_read_b128 v[88:91], v65 offset:6144
	ds_read_b128 v[92:95], v128
	ds_read_b128 v[96:99], v128 offset:2048
	ds_read_b128 v[100:103], v128 offset:4096
	ds_read_b128 v[104:107], v128 offset:6144
	ds_read_b128 v[108:111], v132
	ds_read_b128 v[112:115], v132 offset:2048
	ds_read_b128 v[116:119], v132 offset:4096
	ds_read_b128 v[120:123], v132 offset:6144
	ds_read_b128 v[124:127], v133
	ds_read_b128 v[136:139], v133 offset:2048
	ds_read_b128 v[140:143], v133 offset:4096
	ds_read_b128 v[144:147], v133 offset:6144
	s_waitcnt lgkmcnt(8)
	s_setprio 1
	v_mfma_f32_16x16x32_bf16 v[60:63], v[76:79], v[92:95], v[60:63]
	v_mfma_f32_16x16x32_bf16 v[56:59], v[76:79], v[96:99], v[56:59]
	v_mfma_f32_16x16x32_bf16 v[52:55], v[76:79], v[100:103], v[52:55]
	v_mfma_f32_16x16x32_bf16 v[48:51], v[76:79], v[104:107], v[48:51]
	v_mfma_f32_16x16x32_bf16 v[44:47], v[80:83], v[92:95], v[44:47]
	v_mfma_f32_16x16x32_bf16 v[40:43], v[80:83], v[96:99], v[40:43]
	v_mfma_f32_16x16x32_bf16 v[36:39], v[80:83], v[100:103], v[36:39]
	v_mfma_f32_16x16x32_bf16 v[32:35], v[80:83], v[104:107], v[32:35]
	v_mfma_f32_16x16x32_bf16 v[28:31], v[84:87], v[92:95], v[28:31]
	v_mfma_f32_16x16x32_bf16 v[24:27], v[84:87], v[96:99], v[24:27]
	v_mfma_f32_16x16x32_bf16 v[20:23], v[84:87], v[100:103], v[20:23]
	v_mfma_f32_16x16x32_bf16 v[16:19], v[84:87], v[104:107], v[16:19]
	v_mfma_f32_16x16x32_bf16 v[12:15], v[88:91], v[92:95], v[12:15]
	v_mfma_f32_16x16x32_bf16 v[8:11], v[88:91], v[96:99], v[8:11]
	v_mfma_f32_16x16x32_bf16 v[4:7], v[88:91], v[100:103], v[4:7]
	v_mfma_f32_16x16x32_bf16 v[0:3], v[88:91], v[104:107], v[0:3]
	s_waitcnt lgkmcnt(0)
	v_mfma_f32_16x16x32_bf16 v[60:63], v[108:111], v[124:127], v[60:63]
	v_mfma_f32_16x16x32_bf16 v[56:59], v[108:111], v[136:139], v[56:59]
	v_mfma_f32_16x16x32_bf16 v[52:55], v[108:111], v[140:143], v[52:55]
	v_mfma_f32_16x16x32_bf16 v[48:51], v[108:111], v[144:147], v[48:51]
	v_mfma_f32_16x16x32_bf16 v[44:47], v[112:115], v[124:127], v[44:47]
	v_mfma_f32_16x16x32_bf16 v[40:43], v[112:115], v[136:139], v[40:43]
	v_mfma_f32_16x16x32_bf16 v[36:39], v[112:115], v[140:143], v[36:39]
	v_mfma_f32_16x16x32_bf16 v[32:35], v[112:115], v[144:147], v[32:35]
	v_mfma_f32_16x16x32_bf16 v[28:31], v[116:119], v[124:127], v[28:31]
	v_mfma_f32_16x16x32_bf16 v[24:27], v[116:119], v[136:139], v[24:27]
	v_mfma_f32_16x16x32_bf16 v[20:23], v[116:119], v[140:143], v[20:23]
	v_mfma_f32_16x16x32_bf16 v[16:19], v[116:119], v[144:147], v[16:19]
	v_mfma_f32_16x16x32_bf16 v[12:15], v[120:123], v[124:127], v[12:15]
	v_mfma_f32_16x16x32_bf16 v[8:11], v[120:123], v[136:139], v[8:11]
	v_mfma_f32_16x16x32_bf16 v[4:7], v[120:123], v[140:143], v[4:7]
	v_mfma_f32_16x16x32_bf16 v[0:3], v[120:123], v[144:147], v[0:3]
	s_setprio 0
	s_add_u32 s2, s2, 0x80
	s_addc_u32 s3, s3, 0
	s_cmpk_eq_i32 s2, 0x780
	s_mov_b32 s4, s5
	s_cbranch_scc0 .LBB0_231
	s_lshl_b32 s2, s72, 7
	s_and_b64 s[0:1], s[0:1], exec
	s_waitcnt vmcnt(0)
	s_cselect_b32 s0, s2, -1
	s_cmp_lt_i32 s0, 0
	s_mov_b64 s[4:5], 0x20000
	s_barrier
	s_cbranch_scc1 .LBB0_234
	v_add_u32_e32 v66, s0, v70
	v_lshl_add_u32 v68, s73, 7, v70
	v_ashrrev_i32_e32 v67, 31, v66
	v_ashrrev_i32_e32 v69, 31, v68
	v_lshlrev_b64 v[66:67], 11, v[66:67]
	v_lshlrev_b64 v[68:69], 11, v[68:69]
	v_lshl_add_u64 v[68:69], s[18:19], 0, v[68:69]
	v_lshl_add_u64 v[66:67], s[16:17], 0, v[66:67]
	v_mov_b32_e32 v65, v129
	v_readfirstlane_b32 s0, v75
	v_add_u32_e32 v76, 0x1000, v75
	v_lshl_add_u64 v[68:69], v[68:69], 0, v[64:65]
	v_lshl_add_u64 v[64:65], v[66:67], 0, v[64:65]
	s_mov_b32 m0, s0
	s_mov_b64 s[2:3], 0x10000
	v_readfirstlane_b32 s0, v76
	v_add_u32_e32 v76, 0x2000, v75
	global_load_lds_dwordx4 v[64:65], off
	v_lshl_add_u64 v[66:67], v[64:65], 0, s[2:3]
	s_mov_b32 m0, s0
	v_readfirstlane_b32 s0, v76
	global_load_lds_dwordx4 v[66:67], off
	v_lshl_add_u64 v[66:67], v[64:65], 0, s[4:5]
	s_mov_b32 m0, s0
	v_add_u32_e32 v70, 0x4000, v75
	global_load_lds_dwordx4 v[66:67], off
	v_add_u32_e32 v66, 0x3000, v75
	s_mov_b64 s[48:49], 0x30000
	v_readfirstlane_b32 s0, v66
	v_lshl_add_u64 v[64:65], v[64:65], 0, s[48:49]
	s_mov_b32 m0, s0
	v_readfirstlane_b32 s0, v70
	v_add_u32_e32 v66, 0x5000, v75
	global_load_lds_dwordx4 v[64:65], off
	s_mov_b32 m0, s0
	v_readfirstlane_b32 s0, v66
	v_add_u32_e32 v66, 0x6000, v75
	global_load_lds_dwordx4 v[68:69], off
	v_lshl_add_u64 v[64:65], v[68:69], 0, s[2:3]
	s_mov_b32 m0, s0
	v_readfirstlane_b32 s0, v66
	v_add_u32_e32 v66, 0x7000, v75
	global_load_lds_dwordx4 v[64:65], off
	v_lshl_add_u64 v[64:65], v[68:69], 0, s[4:5]
	s_mov_b32 m0, s0
	v_readfirstlane_b32 s0, v66
	global_load_lds_dwordx4 v[64:65], off
	v_lshl_add_u64 v[64:65], v[68:69], 0, s[48:49]
	s_mov_b32 m0, s0
	s_nop 0
	global_load_lds_dwordx4 v[64:65], off
;     ...
;     const unsigned bo = (kt & 1) * 32768;
;     bf16x8 af[2][4], bfg[2][4];
;     if (NF == 4) {
;       asm volatile(
;           "ds_read_b128 %0, %16\n\tds_read_b128 %1, %16 offset:2048\n\tds_read_b128 %2, %16 offset:4096\n\tds_read_b128 %3, %16 offset:6144\n\t"
;           "ds_read_b128 %4, %17\n\tds_read_b128 %5, %17 offset:2048\n\tds_read_b128 %6, %17 offset:4096\n\tds_read_b128 %7, %17 offset:6144\n\t"
;           "ds_read_b128 %8, %18\n\tds_read_b128 %9, %18 offset:2048\n\tds_read_b128 %10, %18 offset:4096\n\tds_read_b128 %11, %18 offset:6144\n\t"
;           "ds_read_b128 %12, %19\n\tds_read_b128 %13, %19 offset:2048\n\tds_read_b128 %14, %19 offset:4096\n\tds_read_b128 %15, %19 offset:6144\n\t"
;           "s_waitcnt lgkmcnt(0)"
;           : "=&v"(af[0][0]), "=&v"(af[0][1]), "=&v"(af[0][2]), "=&v"(af[0][3]), "=&v"(bfg[0][0]), "=&v"(bfg[0][1]), "=&v"(bfg[0][2]), "=&v"(bfg[0][3]),
;             "=&v"(af[1][0]), "=&v"(af[1][1]), "=&v"(af[1][2]), "=&v"(af[1][3]), "=&v"(bfg[1][0]), "=&v"(bfg[1][1]), "=&v"(bfg[1][2]), "=&v"(bfg[1][3])
;           : "v"(arow + sw0 + bo), "v"(brw + sw0 + bo), "v"(arow + sw1 + bo), "v"(brw + sw1 + bo)
;           : "memory");
;     } else {
;       asm volatile(
;           "ds_read_b128 %0, %12\n\tds_read_b128 %1, %12 offset:2048\n\tds_read_b128 %2, %12 offset:4096\n\tds_read_b128 %3, %12 offset:6144\n\t"
;           "ds_read_b128 %4, %13\n\tds_read_b128 %5, %13 offset:2048\n\t"
;           "ds_read_b128 %6, %14\n\tds_read_b128 %7, %14 offset:2048\n\tds_read_b128 %8, %14 offset:4096\n\tds_read_b128 %9, %14 offset:6144\n\t"
;           "ds_read_b128 %10, %15\n\tds_read_b128 %11, %15 offset:2048\n\t"
;           "s_waitcnt lgkmcnt(0)"
;           : "=&v"(af[0][0]), "=&v"(af[0][1]), "=&v"(af[0][2]), "=&v"(af[0][3]), "=&v"(bfg[0][0]), "=&v"(bfg[0][1]),
;             "=&v"(af[1][0]), "=&v"(af[1][1]), "=&v"(af[1][2]), "=&v"(af[1][3]), "=&v"(bfg[1][0]), "=&v"(bfg[1][1])
;           : "v"(arow + sw0 + bo), "v"(brw + sw0 + bo), "v"(arow + sw1 + bo), "v"(brw + sw1 + bo)
;           : "memory");
;     }
;     __builtin_amdgcn_s_setprio(1);
; #pragma unroll
;     for (int ks = 0; ks < 2; ++ks)
; #pragma unroll
;       for (int m = 0; m < 4; ++m)
; #pragma unroll
;         for (int n = 0; n < NF; ++n) acc[m][n] = MFMA16(af[ks][m], bfg[ks][n], acc[m][n]);
;     __builtin_amdgcn_s_setprio(0);
;   }
.LBB0_234:
	v_add_u32_e32 v128, 0x8000, v71
	v_add_u32_e32 v132, 0x8000, v72
	v_add_u32_e32 v133, 0x8000, v73
	v_add_u32_e32 v134, 0x8000, v74
	ds_read_b128 v[64:67], v128
	ds_read_b128 v[68:71], v128 offset:2048
	ds_read_b128 v[72:75], v128 offset:4096
	ds_read_b128 v[76:79], v128 offset:6144
	ds_read_b128 v[80:83], v132
	ds_read_b128 v[84:87], v132 offset:2048
	ds_read_b128 v[88:91], v132 offset:4096
	ds_read_b128 v[92:95], v132 offset:6144
	ds_read_b128 v[96:99], v133
	ds_read_b128 v[100:103], v133 offset:2048
	ds_read_b128 v[104:107], v133 offset:4096
	ds_read_b128 v[108:111], v133 offset:6144
	ds_read_b128 v[112:115], v134
	ds_read_b128 v[116:119], v134 offset:2048
	ds_read_b128 v[120:123], v134 offset:4096
	ds_read_b128 v[124:127], v134 offset:6144
	s_waitcnt lgkmcnt(8)
	s_setprio 1
	v_mfma_f32_16x16x32_bf16 v[60:63], v[64:67], v[80:83], v[60:63]
	v_mfma_f32_16x16x32_bf16 v[56:59], v[64:67], v[84:87], v[56:59]
	v_mfma_f32_16x16x32_bf16 v[52:55], v[64:67], v[88:91], v[52:55]
	v_mfma_f32_16x16x32_bf16 v[48:51], v[64:67], v[92:95], v[48:51]
	v_mfma_f32_16x16x32_bf16 v[44:47], v[68:71], v[80:83], v[44:47]
	v_mfma_f32_16x16x32_bf16 v[40:43], v[68:71], v[84:87], v[40:43]
	v_mfma_f32_16x16x32_bf16 v[36:39], v[68:71], v[88:91], v[36:39]
	v_mfma_f32_16x16x32_bf16 v[32:35], v[68:71], v[92:95], v[32:35]
	v_mfma_f32_16x16x32_bf16 v[28:31], v[72:75], v[80:83], v[28:31]
	v_mfma_f32_16x16x32_bf16 v[24:27], v[72:75], v[84:87], v[24:27]
	v_mfma_f32_16x16x32_bf16 v[20:23], v[72:75], v[88:91], v[20:23]
	v_mfma_f32_16x16x32_bf16 v[16:19], v[72:75], v[92:95], v[16:19]
	v_mfma_f32_16x16x32_bf16 v[12:15], v[76:79], v[80:83], v[12:15]
	v_mfma_f32_16x16x32_bf16 v[8:11], v[76:79], v[84:87], v[8:11]
	v_mfma_f32_16x16x32_bf16 v[4:7], v[76:79], v[88:91], v[4:7]
	v_mfma_f32_16x16x32_bf16 v[0:3], v[76:79], v[92:95], v[0:3]
	s_waitcnt lgkmcnt(0)
	v_mfma_f32_16x16x32_bf16 v[60:63], v[96:99], v[112:115], v[60:63]
	v_mfma_f32_16x16x32_bf16 v[56:59], v[96:99], v[116:119], v[56:59]
	v_mfma_f32_16x16x32_bf16 v[52:55], v[96:99], v[120:123], v[52:55]
	v_mfma_f32_16x16x32_bf16 v[48:51], v[96:99], v[124:127], v[48:51]
	v_mfma_f32_16x16x32_bf16 v[44:47], v[100:103], v[112:115], v[44:47]
	v_mfma_f32_16x16x32_bf16 v[40:43], v[100:103], v[116:119], v[40:43]
	v_mfma_f32_16x16x32_bf16 v[36:39], v[100:103], v[120:123], v[36:39]
	v_mfma_f32_16x16x32_bf16 v[32:35], v[100:103], v[124:127], v[32:35]
	v_mfma_f32_16x16x32_bf16 v[28:31], v[104:107], v[112:115], v[28:31]
	v_mfma_f32_16x16x32_bf16 v[24:27], v[104:107], v[116:119], v[24:27]
	v_mfma_f32_16x16x32_bf16 v[20:23], v[104:107], v[120:123], v[20:23]
	v_mfma_f32_16x16x32_bf16 v[16:19], v[104:107], v[124:127], v[16:19]
	v_mfma_f32_16x16x32_bf16 v[12:15], v[108:111], v[112:115], v[12:15]
	v_mfma_f32_16x16x32_bf16 v[8:11], v[108:111], v[116:119], v[8:11]
	v_mfma_f32_16x16x32_bf16 v[4:7], v[108:111], v[120:123], v[4:7]
	v_mfma_f32_16x16x32_bf16 v[0:3], v[108:111], v[124:127], v[0:3]
	s_setprio 0
	v_mov_b32_e32 v101, v158
	s_waitcnt lgkmcnt(0)
	s_barrier
	v_readfirstlane_b32 s0, v101
	s_ashr_i32 s49, s0, 6
	s_and_b32 s1, s0, 64
	s_ashr_i32 s0, s0, 1
	s_and_b32 s74, s0, 0xffffffc0
	s_or_b32 s48, s1, s6
	s_add_i32 s74, s74, s7
	v_and_b32_e32 v100, 63, v101
	s_cmpk_gt_i32 s48, 0x1ff
	s_mov_b64 s[0:1], -1
	s_cbranch_scc0 .LBB0_1903
	s_cmpk_gt_u32 s6, 0x3ff
	s_cbranch_scc0 .LBB0_1676
	s_cmpk_gt_u32 s6, 0x5ff
	s_cbranch_scc0 .LBB0_1557
	s_cmpk_gt_u32 s6, 0x7ff
	v_and_b32_e32 v78, 15, v101
	s_cbranch_scc0 .LBB0_1538
	s_cmpk_gt_u32 s6, 0x8ff
	s_cbranch_scc0 .LBB0_1503
	s_cmpk_gt_u32 s48, 0x93f
	s_cbranch_scc0 .LBB0_1276
	s_cmpk_gt_u32 s48, 0xb3f
	s_cbranch_scc0 .LBB0_793
	s_cmpk_gt_u32 s48, 0xd3f
	s_cbranch_scc0 .LBB0_774
	s_cmpk_gt_u32 s48, 0xf3f
	s_cbranch_scc0 .LBB0_291
	s_cmpk_gt_u32 s48, 0x113f
	s_cbranch_scc0 .LBB0_272
	s_cmpk_gt_u32 s48, 0x1d3f
	s_cbranch_scc0 .LBB0_254
	v_lshrrev_b32_e32 v64, 2, v101
	v_add_u32_e32 v65, s48, v78
	v_and_or_b32 v64, v64, 12, s74
	v_add_u32_e32 v128, 0xffffe2c0, v65
	v_cmp_gt_i32_e64 s[0:1], s79, v64
	v_cmp_gt_u32_e32 vcc, 4, v128
	s_and_b64 s[2:3], s[0:1], vcc
	v_lshl_add_u64 v[66:67], v[128:129], 2, s[20:21]
	s_and_saveexec_b64 s[0:1], s[2:3]
	s_cbranch_execz .LBB0_247
	v_ashrrev_i32_e32 v65, 31, v64
	v_lshl_add_u64 v[68:69], v[64:65], 4, v[66:67]
	global_store_dword v[68:69], v60, off
	v_or_b32_e32 v68, 1, v64
	v_ashrrev_i32_e32 v69, 31, v68
	v_lshl_add_u64 v[68:69], v[68:69], 4, v[66:67]
	global_store_dword v[68:69], v61, off
	v_or_b32_e32 v68, 2, v64
	v_ashrrev_i32_e32 v69, 31, v68
	v_lshl_add_u64 v[68:69], v[68:69], 4, v[66:67]
	global_store_dword v[68:69], v62, off
	v_or_b32_e32 v68, 3, v64
	v_ashrrev_i32_e32 v69, 31, v68
	v_lshl_add_u64 v[68:69], v[68:69], 4, v[66:67]
	global_store_dword v[68:69], v63, off

; DI float bf2f(bfr b) { return __uint_as_float(((unsigned)b) << 16); }
; DI bfr f2bf(float x) { return (bfr)(pack2(x, 0.f) & 0xFFFFu); }
; DI void lru_tile(const Params& p, int layer, int isP, int sq, int tile, int nb, int pass, char*) {
;     ...
;     for (int w = 0; w < wid; ++w) h = ab[(w * 64 + c) * 2] * h + ab[(w * 64 + c) * 2 + 1];
; #pragma unroll
;     for (int tt = 0; tt < 16; ++tt) {
;       const int t = wid * 16 + tt;
;       h = as_[t * 64 + c] * h + bs_[t * 64 + c];
;       if (t0 + t < T) {
;         const long idx = (long)(rowbase + t0 + t) * 512 + ch0 + c;
;         gby[idx] = f2bf(h * bf2f(gby[idx]));
;         if (t0 + t == T - 1) {
;           if (isP) p.out[O_LRUP + (long)(layer * NB_P + sq) * 512 + ch0 + c] = h;
;           else p.out[O_LRUS + (long)(layer * NB_S + sq) * 512 + ch0 + c] = h;
;         }
;       }
;     }
.LBB0_4798:
	s_add_i32 s0, s44, s46
	s_lshl_b32 s1, s43, 1
	s_add_u32 s2, s55, s1
	s_addc_u32 s3, s56, 0
	s_add_i32 s1, s10, s44
	v_lshl_add_u64 v[2:3], s[2:3], 0, v[128:129]
	s_cmpk_lt_i32 s1, 0x1000
	s_cbranch_scc0 .Llru1_slow
	s_add_i32 s2, s10, s0
	s_ashr_i32 s3, s2, 31
	s_lshl_b64 s[2:3], s[2:3], 10
	v_lshl_add_u64 v[2:3], v[2:3], 0, s[2:3]
	s_mov_b64 s[4:5], 0x1000
	v_lshl_add_u64 v[6:7], v[2:3], 0, s[4:5]
	v_lshl_add_u64 v[8:9], v[6:7], 0, s[4:5]
	v_lshl_add_u64 v[10:11], v[8:9], 0, s[4:5]
	global_load_ushort v12, v[2:3], off
	global_load_ushort v13, v[2:3], off offset:1024
	global_load_ushort v14, v[2:3], off offset:2048
	global_load_ushort v15, v[2:3], off offset:3072
	global_load_ushort v16, v[6:7], off
	global_load_ushort v17, v[6:7], off offset:1024
	global_load_ushort v18, v[6:7], off offset:2048
	global_load_ushort v19, v[6:7], off offset:3072
	global_load_ushort v20, v[8:9], off
	global_load_ushort v21, v[8:9], off offset:1024
	global_load_ushort v22, v[8:9], off offset:2048
	global_load_ushort v23, v[8:9], off offset:3072
	global_load_ushort v24, v[10:11], off
	global_load_ushort v25, v[10:11], off offset:1024
	global_load_ushort v26, v[10:11], off offset:2048
	global_load_ushort v27, v[10:11], off offset:3072
	ds_read2st64_b32 v[52:53], v1 offset1:131
	ds_read2st64_b32 v[54:55], v1 offset0:1 offset1:132
	ds_read2st64_b32 v[56:57], v1 offset0:2 offset1:133
	ds_read2st64_b32 v[58:59], v1 offset0:3 offset1:134
	ds_read2st64_b32 v[60:61], v1 offset0:4 offset1:135
	ds_read2st64_b32 v[62:63], v1 offset0:5 offset1:136
	ds_read2st64_b32 v[64:65], v1 offset0:6 offset1:137
	ds_read2st64_b32 v[66:67], v1 offset0:7 offset1:138
	ds_read2st64_b32 v[68:69], v1 offset0:8 offset1:139
	ds_read2st64_b32 v[70:71], v1 offset0:9 offset1:140
	ds_read2st64_b32 v[72:73], v1 offset0:10 offset1:141
	ds_read2st64_b32 v[74:75], v1 offset0:11 offset1:142
	ds_read2st64_b32 v[76:77], v1 offset0:12 offset1:143
	ds_read2st64_b32 v[78:79], v1 offset0:13 offset1:144
	ds_read2st64_b32 v[80:81], v1 offset0:14 offset1:145
	ds_read2st64_b32 v[82:83], v1 offset0:15 offset1:146
	s_waitcnt lgkmcnt(15)
	v_fmac_f32_e32 v53, v36, v52
	s_waitcnt lgkmcnt(14)
	v_fmac_f32_e32 v55, v53, v54
	s_waitcnt lgkmcnt(13)
	v_fmac_f32_e32 v57, v55, v56
	s_waitcnt lgkmcnt(12)
	v_fmac_f32_e32 v59, v57, v58
	s_waitcnt lgkmcnt(11)
	v_fmac_f32_e32 v61, v59, v60
	s_waitcnt lgkmcnt(10)
	v_fmac_f32_e32 v63, v61, v62
	s_waitcnt lgkmcnt(9)
	v_fmac_f32_e32 v65, v63, v64
	s_waitcnt lgkmcnt(8)
	v_fmac_f32_e32 v67, v65, v66
	s_waitcnt lgkmcnt(7)
	v_fmac_f32_e32 v69, v67, v68
	s_waitcnt lgkmcnt(6)
	v_fmac_f32_e32 v71, v69, v70
	s_waitcnt lgkmcnt(5)
	v_fmac_f32_e32 v73, v71, v72
	s_waitcnt lgkmcnt(4)
	v_fmac_f32_e32 v75, v73, v74
	s_waitcnt lgkmcnt(3)
	v_fmac_f32_e32 v77, v75, v76
	s_waitcnt lgkmcnt(2)
	v_fmac_f32_e32 v79, v77, v78
	s_waitcnt lgkmcnt(1)
	v_fmac_f32_e32 v81, v79, v80
	s_waitcnt lgkmcnt(0)
	v_fmac_f32_e32 v83, v81, v82
	s_waitcnt vmcnt(15)
	v_lshlrev_b32_e32 v12, 16, v12
	v_mul_f32_e32 v12, v53, v12
	v_cvt_pk_bf16_f32 v12, v12, v12
	global_store_short v[2:3], v12, off
	s_waitcnt vmcnt(15)
	v_lshlrev_b32_e32 v13, 16, v13
	v_mul_f32_e32 v13, v55, v13
	v_cvt_pk_bf16_f32 v13, v13, v13
	global_store_short v[2:3], v13, off offset:1024
	s_waitcnt vmcnt(15)
	v_lshlrev_b32_e32 v14, 16, v14
	v_mul_f32_e32 v14, v57, v14
	v_cvt_pk_bf16_f32 v14, v14, v14
	global_store_short v[2:3], v14, off offset:2048
	s_waitcnt vmcnt(15)
	v_lshlrev_b32_e32 v15, 16, v15
	v_mul_f32_e32 v15, v59, v15
	v_cvt_pk_bf16_f32 v15, v15, v15
	global_store_short v[2:3], v15, off offset:3072
	s_waitcnt vmcnt(15)
	v_lshlrev_b32_e32 v16, 16, v16
	v_mul_f32_e32 v16, v61, v16
	v_cvt_pk_bf16_f32 v16, v16, v16
	global_store_short v[6:7], v16, off
	s_waitcnt vmcnt(15)
	v_lshlrev_b32_e32 v17, 16, v17
	v_mul_f32_e32 v17, v63, v17
	v_cvt_pk_bf16_f32 v17, v17, v17
	global_store_short v[6:7], v17, off offset:1024
	s_waitcnt vmcnt(15)
	v_lshlrev_b32_e32 v18, 16, v18
	v_mul_f32_e32 v18, v65, v18
	v_cvt_pk_bf16_f32 v18, v18, v18
	global_store_short v[6:7], v18, off offset:2048
	s_waitcnt vmcnt(15)
	v_lshlrev_b32_e32 v19, 16, v19
	v_mul_f32_e32 v19, v67, v19
	v_cvt_pk_bf16_f32 v19, v19, v19
	global_store_short v[6:7], v19, off offset:3072
	s_waitcnt vmcnt(15)
	v_lshlrev_b32_e32 v20, 16, v20
	v_mul_f32_e32 v20, v69, v20
	v_cvt_pk_bf16_f32 v20, v20, v20
	global_store_short v[8:9], v20, off
	s_waitcnt vmcnt(15)
	v_lshlrev_b32_e32 v21, 16, v21
	v_mul_f32_e32 v21, v71, v21
	v_cvt_pk_bf16_f32 v21, v21, v21
	global_store_short v[8:9], v21, off offset:1024
	s_waitcnt vmcnt(15)
	v_lshlrev_b32_e32 v22, 16, v22
	v_mul_f32_e32 v22, v73, v22
	v_cvt_pk_bf16_f32 v22, v22, v22
	global_store_short v[8:9], v22, off offset:2048
	s_waitcnt vmcnt(15)
	v_lshlrev_b32_e32 v23, 16, v23
	v_mul_f32_e32 v23, v75, v23
	v_cvt_pk_bf16_f32 v23, v23, v23
	global_store_short v[8:9], v23, off offset:3072
	s_waitcnt vmcnt(15)
	v_lshlrev_b32_e32 v24, 16, v24
	v_mul_f32_e32 v24, v77, v24
	v_cvt_pk_bf16_f32 v24, v24, v24
	global_store_short v[10:11], v24, off
	s_waitcnt vmcnt(15)
	v_lshlrev_b32_e32 v25, 16, v25
	v_mul_f32_e32 v25, v79, v25
	v_cvt_pk_bf16_f32 v25, v25, v25
	global_store_short v[10:11], v25, off offset:1024
	s_waitcnt vmcnt(15)
	v_lshlrev_b32_e32 v26, 16, v26
	v_mul_f32_e32 v26, v81, v26
	v_cvt_pk_bf16_f32 v26, v26, v26
	global_store_short v[10:11], v26, off offset:2048
	s_waitcnt vmcnt(15)
	v_lshlrev_b32_e32 v27, 16, v27
	v_mul_f32_e32 v27, v83, v27
	v_cvt_pk_bf16_f32 v27, v27, v27
	global_store_short v[10:11], v27, off offset:3072
	s_branch .LBB0_4487

;   const int tid = get_tid(), wid = __builtin_amdgcn_readfirstlane(tid >> 6), lane = tid & 63, wr = wid >> 1, wc = wid & 1, fr = lane & 15, fq = lane >> 4;
;   const int r0 = tid >> 3;
;   const int cg = ((tid & 7) ^ (r0 & 7)) * 8;
;   const bfr* ga = A + (long)(brow + r0) * lda + cg;
;   const bfr* gb = Bt + (long)(bcol + r0) * ldb + cg;
;   const long a32 = (long)32 * lda, b32 = (long)32 * ldb;
;   const int nk = K / 64;
;   auto stage = [&](int kt, int buf) {
;     char* SA = smem + buf * 32768;
;     char* SB = SA + 16384;
; #pragma unroll
;     for (int i = 0; i < 4; ++i)
;       __builtin_amdgcn_global_load_lds((const unsigned*)(ga + i * a32 + kt * 64), (unsigned*)(SA + tid * 16 + i * 4096), 16, 0, 0);
; #pragma unroll
;     for (int i = 0; i < NF; ++i)
;       __builtin_amdgcn_global_load_lds((const unsigned*)(gb + i * b32 + kt * 64), (unsigned*)(SB + tid * 16 + i * 4096), 16, 0, 0);
;   };
;   if (!chained || first) {
;     asm volatile("s_waitcnt vmcnt(0)" ::: "memory");
;     __syncthreads();
;     stage(0, 0);
;   }
;   const unsigned lds0 = (unsigned)(size_t)smem;
;   const unsigned sw0 = (unsigned)((fq ^ (fr & 7)) * 16), sw1 = (unsigned)(((4 + fq) ^ (fr & 7)) * 16);
;   const unsigned arow = lds0 + (wr * 64 + fr) * 128, brw = lds0 + 16384 + (wc * NF * 16 + fr) * 128;
;   for (int kt = 0; kt < nk; ++kt) {
;     asm volatile("s_waitcnt vmcnt(0)" ::: "memory");
;     __builtin_amdgcn_s_barrier();
;     if (kt + 1 < nk) stage(kt + 1, (kt + 1) & 1);
;     else if (chained && nbrow >= 0) {
;       const bfr* na = (nA ? nA : A) + (long)(nbrow + r0) * lda + cg;
;       const bfr* nb = (nBt ? nBt : Bt) + (long)(nbcol + r0) * ldb + cg;
; #pragma unroll
;       for (int i = 0; i < 4; ++i)
;         __builtin_amdgcn_global_load_lds((const unsigned*)(na + i * a32), (unsigned*)(smem + tid * 16 + i * 4096), 16, 0, 0);
; #pragma unroll
;       for (int i = 0; i < NF; ++i)
;         __builtin_amdgcn_global_load_lds((const unsigned*)(nb + i * b32), (unsigned*)(smem + 16384 + tid * 16 + i * 4096), 16, 0, 0);
;     }
;     const unsigned bo = (kt & 1) * 32768;
;     bf16x8 af[2][4], bfg[2][4];
;     if (NF == 4) {
;       asm volatile(
;           "ds_read_b128 %0, %16\n\tds_read_b128 %1, %16 offset:2048\n\tds_read_b128 %2, %16 offset:4096\n\tds_read_b128 %3, %16 offset:6144\n\t"
.LBB0_4964:
	s_add_i32 s47, s47, 1
	s_cmpk_eq_i32 s18, 0x1000
	s_cselect_b64 s[24:25], -1, 0
	s_and_b64 s[26:27], s[24:25], exec
	s_cselect_b32 s26, s46, s17
	s_cmp_lg_u32 0x80, -1
	v_and_b32_e32 v6, 15, v5
	s_cselect_b32 s27, 0x80, 0
	v_and_or_b32 v9, s48, 64, v6
	s_add_i32 s28, s27, 0x4000
	v_lshl_add_u32 v9, v9, 7, s28
	s_lshr_b32 s28, s48, 1
	v_lshrrev_b32_e32 v7, 4, v5
	v_bfe_u32 v8, v5, 4, 2
	s_and_b32 s28, s28, 0x1ffffc0
	v_and_b32_e32 v5, 7, v5
	v_add_u32_e32 v75, 0x80, v4
	v_or_b32_e32 v6, s28, v6
	v_bitop3_b32 v8, v8, v5, 4 bitop3:0x36
	v_bitop3_b32 v5, v7, v5, 3 bitop3:0x6c
	v_add_u32_e32 v10, 0x8000, v75
	v_lshl_add_u32 v6, v6, 7, s27
	v_lshlrev_b32_e32 v8, 4, v8
	v_lshlrev_b32_e32 v5, 4, v5
	s_mov_b64 s[48:49], 0x80
	v_readfirstlane_b32 s29, v10
	v_add_u32_e32 v10, 0x9000, v75
	v_add_u32_e32 v4, v6, v5
	v_add_u32_e32 v5, v9, v5
	v_add_u32_e32 v6, v6, v8
	v_add_u32_e32 v7, v9, v8
	v_lshl_add_u64 v[8:9], v[2:3], 0, s[48:49]
	s_mov_b32 m0, s29
	s_mov_b64 s[50:51], 0x8080
	v_readfirstlane_b32 s27, v10
	v_add_u32_e32 v10, 0xa000, v75
	s_waitcnt vmcnt(0)
	s_barrier
	global_load_lds_dwordx4 v[8:9], off
	v_lshl_add_u64 v[8:9], v[2:3], 0, s[50:51]
	s_mov_b32 m0, s27
	s_mov_b64 s[52:53], 0x10080
	v_readfirstlane_b32 s28, v10
	v_add_u32_e32 v10, 0xb000, v75
	global_load_lds_dwordx4 v[8:9], off
	v_lshl_add_u64 v[8:9], v[2:3], 0, s[52:53]
	s_mov_b32 m0, s28
	s_mov_b64 s[54:55], 0x18080
	v_readfirstlane_b32 s30, v10
	v_add_u32_e32 v10, 0xc000, v75
	global_load_lds_dwordx4 v[8:9], off
	v_lshl_add_u64 v[8:9], v[2:3], 0, s[54:55]
	s_mov_b32 m0, s30
	v_readfirstlane_b32 s31, v10
	v_add_u32_e32 v10, 0xd000, v75
	global_load_lds_dwordx4 v[8:9], off
	v_lshl_add_u64 v[8:9], v[0:1], 0, s[48:49]
	s_mov_b32 m0, s31
	v_readfirstlane_b32 s48, v10
	v_add_u32_e32 v10, 0xe000, v75
	global_load_lds_dwordx4 v[8:9], off
	v_lshl_add_u64 v[8:9], v[0:1], 0, s[50:51]
	s_mov_b32 m0, s48
	v_readfirstlane_b32 s49, v10
	v_add_u32_e32 v10, 0xf000, v75
	global_load_lds_dwordx4 v[8:9], off
	v_lshl_add_u64 v[8:9], v[0:1], 0, s[52:53]
	s_mov_b32 m0, s49
	v_readfirstlane_b32 s50, v10
	global_load_lds_dwordx4 v[8:9], off
	v_lshl_add_u64 v[8:9], v[0:1], 0, s[54:55]
	s_mov_b32 m0, s50
	s_nop 0
	global_load_lds_dwordx4 v[8:9], off
	ds_read_b128 v[8:11], v4
	ds_read_b128 v[12:15], v4 offset:2048
	ds_read_b128 v[16:19], v4 offset:4096
	ds_read_b128 v[20:23], v4 offset:6144
	ds_read_b128 v[24:27], v5
	ds_read_b128 v[28:31], v5 offset:2048
	ds_read_b128 v[32:35], v5 offset:4096
	ds_read_b128 v[36:39], v5 offset:6144
	ds_read_b128 v[40:43], v6
	ds_read_b128 v[44:47], v6 offset:2048
	ds_read_b128 v[48:51], v6 offset:4096
	ds_read_b128 v[52:55], v6 offset:6144
	ds_read_b128 v[56:59], v7
	ds_read_b128 v[60:63], v7 offset:2048
	ds_read_b128 v[110:113], v7 offset:4096
	ds_read_b128 v[114:117], v7 offset:6144
	s_waitcnt lgkmcnt(8)
	s_setprio 1
	v_mfma_f32_16x16x32_bf16 v[118:121], v[8:11], v[24:27], 0
	v_mfma_f32_16x16x32_bf16 v[122:125], v[8:11], v[28:31], 0
	v_mfma_f32_16x16x32_bf16 v[132:135], v[8:11], v[32:35], 0
	v_mfma_f32_16x16x32_bf16 v[8:11], v[8:11], v[36:39], 0
	v_mfma_f32_16x16x32_bf16 v[136:139], v[12:15], v[24:27], 0
	v_mfma_f32_16x16x32_bf16 v[140:143], v[12:15], v[28:31], 0
	v_mfma_f32_16x16x32_bf16 v[144:147], v[12:15], v[32:35], 0
	v_mfma_f32_16x16x32_bf16 v[12:15], v[12:15], v[36:39], 0
	v_mfma_f32_16x16x32_bf16 v[148:151], v[16:19], v[24:27], 0
	v_mfma_f32_16x16x32_bf16 v[152:155], v[16:19], v[28:31], 0
	v_mfma_f32_16x16x32_bf16 v[180:183], v[16:19], v[32:35], 0
	v_mfma_f32_16x16x32_bf16 v[16:19], v[16:19], v[36:39], 0
	v_mfma_f32_16x16x32_bf16 v[24:27], v[20:23], v[24:27], 0
	v_mfma_f32_16x16x32_bf16 v[28:31], v[20:23], v[28:31], 0
	v_mfma_f32_16x16x32_bf16 v[32:35], v[20:23], v[32:35], 0
	v_mfma_f32_16x16x32_bf16 v[20:23], v[20:23], v[36:39], 0
	s_waitcnt lgkmcnt(0)
	v_mfma_f32_16x16x32_bf16 v[36:39], v[40:43], v[56:59], v[118:121]
	v_mfma_f32_16x16x32_bf16 v[120:123], v[40:43], v[60:63], v[122:125]
	v_mfma_f32_16x16x32_bf16 v[124:127], v[40:43], v[110:113], v[132:135]
	v_mfma_f32_16x16x32_bf16 v[8:11], v[40:43], v[114:117], v[8:11]
	v_mfma_f32_16x16x32_bf16 v[40:43], v[44:47], v[56:59], v[136:139]
	v_mfma_f32_16x16x32_bf16 v[132:135], v[44:47], v[60:63], v[140:143]
	v_mfma_f32_16x16x32_bf16 v[136:139], v[44:47], v[110:113], v[144:147]
	v_mfma_f32_16x16x32_bf16 v[12:15], v[44:47], v[114:117], v[12:15]
	v_mfma_f32_16x16x32_bf16 v[44:47], v[48:51], v[56:59], v[148:151]
	v_mfma_f32_16x16x32_bf16 v[16:19], v[48:51], v[114:117], v[16:19]
	v_mfma_f32_16x16x32_bf16 v[24:27], v[52:55], v[56:59], v[24:27]
	v_mfma_f32_16x16x32_bf16 v[28:31], v[52:55], v[60:63], v[28:31]
	v_mfma_f32_16x16x32_bf16 v[32:35], v[52:55], v[110:113], v[32:35]
	v_mfma_f32_16x16x32_bf16 v[20:23], v[52:55], v[114:117], v[20:23]
	v_mfma_f32_16x16x32_bf16 v[140:143], v[48:51], v[60:63], v[152:155]
	v_mfma_f32_16x16x32_bf16 v[144:147], v[48:51], v[110:113], v[180:183]
	s_setprio 0
	s_mov_b64 s[56:57], 0x100
	v_readfirstlane_b32 s53, v75
	v_add_u32_e32 v76, 0x1000, v75
	v_lshl_add_u64 v[48:49], v[2:3], 0, s[56:57]
	s_mov_b32 m0, s53
	s_mov_b64 vcc, 0x8100
	v_readfirstlane_b32 s51, v76
	v_add_u32_e32 v77, 0x2000, v75
	s_waitcnt vmcnt(0)
	s_barrier
;     ...
;   for (int kt = 0; kt < nk; ++kt) {
;     asm volatile("s_waitcnt vmcnt(0)" ::: "memory");
;     __builtin_amdgcn_s_barrier();
;     if (kt + 1 < nk) stage(kt + 1, (kt + 1) & 1);
;     else if (chained && nbrow >= 0) {
;       const bfr* na = (nA ? nA : A) + (long)(nbrow + r0) * lda + cg;
;       const bfr* nb = (nBt ? nBt : Bt) + (long)(nbcol + r0) * ldb + cg;
; #pragma unroll
;       for (int i = 0; i < 4; ++i)
;         __builtin_amdgcn_global_load_lds((const unsigned*)(na + i * a32), (unsigned*)(smem + tid * 16 + i * 4096), 16, 0, 0);
; #pragma unroll
;       for (int i = 0; i < NF; ++i)
;         __builtin_amdgcn_global_load_lds((const unsigned*)(nb + i * b32), (unsigned*)(smem + 16384 + tid * 16 + i * 4096), 16, 0, 0);
;     }
;     const unsigned bo = (kt & 1) * 32768;
;     bf16x8 af[2][4], bfg[2][4];
;     if (NF == 4) {
;       asm volatile(
;           "ds_read_b128 %0, %16\n\tds_read_b128 %1, %16 offset:2048\n\tds_read_b128 %2, %16 offset:4096\n\tds_read_b128 %3, %16 offset:6144\n\t"
;           "ds_read_b128 %4, %17\n\tds_read_b128 %5, %17 offset:2048\n\tds_read_b128 %6, %17 offset:4096\n\tds_read_b128 %7, %17 offset:6144\n\t"
;           "ds_read_b128 %8, %18\n\tds_read_b128 %9, %18 offset:2048\n\tds_read_b128 %10, %18 offset:4096\n\tds_read_b128 %11, %18 offset:6144\n\t"
;           "ds_read_b128 %12, %19\n\tds_read_b128 %13, %19 offset:2048\n\tds_read_b128 %14, %19 offset:4096\n\tds_read_b128 %15, %19 offset:6144\n\t"
;           "s_waitcnt lgkmcnt(0)"
;           : "=&v"(af[0][0]), "=&v"(af[0][1]), "=&v"(af[0][2]), "=&v"(af[0][3]), "=&v"(bfg[0][0]), "=&v"(bfg[0][1]), "=&v"(bfg[0][2]), "=&v"(bfg[0][3]),
;             "=&v"(af[1][0]), "=&v"(af[1][1]), "=&v"(af[1][2]), "=&v"(af[1][3]), "=&v"(bfg[1][0]), "=&v"(bfg[1][1]), "=&v"(bfg[1][2]), "=&v"(bfg[1][3])
;           : "v"(arow + sw0 + bo), "v"(brw + sw0 + bo), "v"(arow + sw1 + bo), "v"(brw + sw1 + bo)
;           : "memory");
;     } else {
;       asm volatile(
;           "ds_read_b128 %0, %12\n\tds_read_b128 %1, %12 offset:2048\n\tds_read_b128 %2, %12 offset:4096\n\tds_read_b128 %3, %12 offset:6144\n\t"
;           "ds_read_b128 %4, %13\n\tds_read_b128 %5, %13 offset:2048\n\t"
;           "ds_read_b128 %6, %14\n\tds_read_b128 %7, %14 offset:2048\n\tds_read_b128 %8, %14 offset:4096\n\tds_read_b128 %9, %14 offset:6144\n\t"
	global_load_lds_dwordx4 v[48:49], off
	v_lshl_add_u64 v[48:49], v[2:3], 0, vcc
	s_mov_b32 m0, s51
	s_mov_b64 s[64:65], 0x10100
	v_readfirstlane_b32 s52, v77
	v_add_u32_e32 v110, 0x3000, v75
	global_load_lds_dwordx4 v[48:49], off
	v_lshl_add_u64 v[48:49], v[2:3], 0, s[64:65]
	s_mov_b32 m0, s52
	s_mov_b64 s[66:67], 0x18100
	v_readfirstlane_b32 s54, v110
	v_add_u32_e32 v112, 0x4000, v75
	global_load_lds_dwordx4 v[48:49], off
	v_lshl_add_u64 v[48:49], v[2:3], 0, s[66:67]
	s_mov_b32 m0, s54
	v_readfirstlane_b32 s55, v112
	v_add_u32_e32 v114, 0x5000, v75
	global_load_lds_dwordx4 v[48:49], off
	v_lshl_add_u64 v[48:49], v[0:1], 0, s[56:57]
	s_mov_b32 m0, s55
	v_readfirstlane_b32 s56, v114
	v_add_u32_e32 v116, 0x6000, v75
	global_load_lds_dwordx4 v[48:49], off
	v_lshl_add_u64 v[48:49], v[0:1], 0, vcc
	s_mov_b32 m0, s56
	v_readfirstlane_b32 s57, v116
	v_add_u32_e32 v118, 0x7000, v75
	global_load_lds_dwordx4 v[48:49], off
	v_lshl_add_u64 v[48:49], v[0:1], 0, s[64:65]
	s_mov_b32 m0, s57
	v_readfirstlane_b32 s58, v118
	global_load_lds_dwordx4 v[48:49], off
	v_lshl_add_u64 v[48:49], v[0:1], 0, s[66:67]
	s_mov_b32 m0, s58
	v_add_u32_e32 v111, 0x8000, v4
	global_load_lds_dwordx4 v[48:49], off
	v_add_u32_e32 v113, 0x8000, v5
	v_add_u32_e32 v115, 0x8000, v6
	v_add_u32_e32 v117, 0x8000, v7
	ds_read_b128 v[48:51], v111
	ds_read_b128 v[52:55], v111 offset:2048
	ds_read_b128 v[56:59], v111 offset:4096
	ds_read_b128 v[60:63], v111 offset:6144
	ds_read_b128 v[148:151], v113
	ds_read_b128 v[152:155], v113 offset:2048
	ds_read_b128 v[180:183], v113 offset:4096
	ds_read_b128 v[184:187], v113 offset:6144
	ds_read_b128 v[188:191], v115
	ds_read_b128 v[192:195], v115 offset:2048
	ds_read_b128 v[196:199], v115 offset:4096
	ds_read_b128 v[200:203], v115 offset:6144
	ds_read_b128 v[204:207], v117
	ds_read_b128 v[208:211], v117 offset:2048
	ds_read_b128 v[212:215], v117 offset:4096
	ds_read_b128 v[216:219], v117 offset:6144
	s_waitcnt lgkmcnt(8)
	s_setprio 1
	v_mfma_f32_16x16x32_bf16 v[36:39], v[48:51], v[148:151], v[36:39]
	v_mfma_f32_16x16x32_bf16 v[120:123], v[48:51], v[152:155], v[120:123]
	v_mfma_f32_16x16x32_bf16 v[124:127], v[48:51], v[180:183], v[124:127]
	v_mfma_f32_16x16x32_bf16 v[8:11], v[48:51], v[184:187], v[8:11]
	v_mfma_f32_16x16x32_bf16 v[40:43], v[52:55], v[148:151], v[40:43]
	v_mfma_f32_16x16x32_bf16 v[48:51], v[52:55], v[152:155], v[132:135]
	v_mfma_f32_16x16x32_bf16 v[132:135], v[52:55], v[180:183], v[136:139]
	v_mfma_f32_16x16x32_bf16 v[12:15], v[52:55], v[184:187], v[12:15]
	v_mfma_f32_16x16x32_bf16 v[44:47], v[56:59], v[148:151], v[44:47]
	v_mfma_f32_16x16x32_bf16 v[52:55], v[56:59], v[152:155], v[140:143]
	v_mfma_f32_16x16x32_bf16 v[16:19], v[56:59], v[184:187], v[16:19]
	v_mfma_f32_16x16x32_bf16 v[24:27], v[60:63], v[148:151], v[24:27]
	v_mfma_f32_16x16x32_bf16 v[28:31], v[60:63], v[152:155], v[28:31]
	v_mfma_f32_16x16x32_bf16 v[32:35], v[60:63], v[180:183], v[32:35]
	v_mfma_f32_16x16x32_bf16 v[20:23], v[60:63], v[184:187], v[20:23]
	v_mfma_f32_16x16x32_bf16 v[136:139], v[56:59], v[180:183], v[144:147]
	s_waitcnt lgkmcnt(0)
	v_mfma_f32_16x16x32_bf16 v[36:39], v[188:191], v[204:207], v[36:39]
	v_mfma_f32_16x16x32_bf16 v[56:59], v[188:191], v[208:211], v[120:123]
	v_mfma_f32_16x16x32_bf16 v[60:63], v[188:191], v[212:215], v[124:127]
	v_mfma_f32_16x16x32_bf16 v[8:11], v[188:191], v[216:219], v[8:11]
	v_mfma_f32_16x16x32_bf16 v[40:43], v[192:195], v[204:207], v[40:43]
	v_mfma_f32_16x16x32_bf16 v[48:51], v[192:195], v[208:211], v[48:51]
	v_mfma_f32_16x16x32_bf16 v[12:15], v[192:195], v[216:219], v[12:15]
	v_mfma_f32_16x16x32_bf16 v[44:47], v[196:199], v[204:207], v[44:47]
	v_mfma_f32_16x16x32_bf16 v[52:55], v[196:199], v[208:211], v[52:55]
	v_mfma_f32_16x16x32_bf16 v[16:19], v[196:199], v[216:219], v[16:19]
	v_mfma_f32_16x16x32_bf16 v[24:27], v[200:203], v[204:207], v[24:27]
	v_mfma_f32_16x16x32_bf16 v[28:31], v[200:203], v[208:211], v[28:31]
	v_mfma_f32_16x16x32_bf16 v[32:35], v[200:203], v[212:215], v[32:35]
	v_mfma_f32_16x16x32_bf16 v[20:23], v[200:203], v[216:219], v[20:23]
	v_mfma_f32_16x16x32_bf16 v[120:123], v[192:195], v[212:215], v[132:135]
	v_mfma_f32_16x16x32_bf16 v[124:127], v[196:199], v[212:215], v[136:139]
	s_setprio 0
	s_mov_b64 s[64:65], 0x180
	s_mov_b32 m0, s29
	v_lshl_add_u64 v[132:133], v[2:3], 0, s[64:65]
	s_mov_b64 s[66:67], 0x8180
	s_waitcnt vmcnt(0)
	s_barrier
;     ...
;   for (int kt = 0; kt < nk; ++kt) {
;     asm volatile("s_waitcnt vmcnt(0)" ::: "memory");
;     __builtin_amdgcn_s_barrier();
;     if (kt + 1 < nk) stage(kt + 1, (kt + 1) & 1);
;     else if (chained && nbrow >= 0) {
;       const bfr* na = (nA ? nA : A) + (long)(nbrow + r0) * lda + cg;
;       const bfr* nb = (nBt ? nBt : Bt) + (long)(nbcol + r0) * ldb + cg;
; #pragma unroll
;       for (int i = 0; i < 4; ++i)
;         __builtin_amdgcn_global_load_lds((const unsigned*)(na + i * a32), (unsigned*)(smem + tid * 16 + i * 4096), 16, 0, 0);
; #pragma unroll
;       for (int i = 0; i < NF; ++i)
;         __builtin_amdgcn_global_load_lds((const unsigned*)(nb + i * b32), (unsigned*)(smem + 16384 + tid * 16 + i * 4096), 16, 0, 0);
;     }
;     const unsigned bo = (kt & 1) * 32768;
;     bf16x8 af[2][4], bfg[2][4];
;     if (NF == 4) {
;       asm volatile(
;           "ds_read_b128 %0, %16\n\tds_read_b128 %1, %16 offset:2048\n\tds_read_b128 %2, %16 offset:4096\n\tds_read_b128 %3, %16 offset:6144\n\t"
;           "ds_read_b128 %4, %17\n\tds_read_b128 %5, %17 offset:2048\n\tds_read_b128 %6, %17 offset:4096\n\tds_read_b128 %7, %17 offset:6144\n\t"
;           "ds_read_b128 %8, %18\n\tds_read_b128 %9, %18 offset:2048\n\tds_read_b128 %10, %18 offset:4096\n\tds_read_b128 %11, %18 offset:6144\n\t"
;           "ds_read_b128 %12, %19\n\tds_read_b128 %13, %19 offset:2048\n\tds_read_b128 %14, %19 offset:4096\n\tds_read_b128 %15, %19 offset:6144\n\t"
;           "s_waitcnt lgkmcnt(0)"
;           : "=&v"(af[0][0]), "=&v"(af[0][1]), "=&v"(af[0][2]), "=&v"(af[0][3]), "=&v"(bfg[0][0]), "=&v"(bfg[0][1]), "=&v"(bfg[0][2]), "=&v"(bfg[0][3]),
;             "=&v"(af[1][0]), "=&v"(af[1][1]), "=&v"(af[1][2]), "=&v"(af[1][3]), "=&v"(bfg[1][0]), "=&v"(bfg[1][1]), "=&v"(bfg[1][2]), "=&v"(bfg[1][3])
;           : "v"(arow + sw0 + bo), "v"(brw + sw0 + bo), "v"(arow + sw1 + bo), "v"(brw + sw1 + bo)
;           : "memory");
;     } else {
;       asm volatile(
;           "ds_read_b128 %0, %12\n\tds_read_b128 %1, %12 offset:2048\n\tds_read_b128 %2, %12 offset:4096\n\tds_read_b128 %3, %12 offset:6144\n\t"
;           "ds_read_b128 %4, %13\n\tds_read_b128 %5, %13 offset:2048\n\t"
;           "ds_read_b128 %6, %14\n\tds_read_b128 %7, %14 offset:2048\n\tds_read_b128 %8, %14 offset:4096\n\tds_read_b128 %9, %14 offset:6144\n\t"
	global_load_lds_dwordx4 v[132:133], off
	v_lshl_add_u64 v[132:133], v[2:3], 0, s[66:67]
	s_mov_b32 m0, s27
	s_mov_b64 vcc, 0x10180
	global_load_lds_dwordx4 v[132:133], off
	v_lshl_add_u64 v[132:133], v[2:3], 0, vcc
	s_mov_b32 m0, s28
	s_mov_b64 s[68:69], 0x18180
	global_load_lds_dwordx4 v[132:133], off
	v_lshl_add_u64 v[132:133], v[2:3], 0, s[68:69]
	s_mov_b32 m0, s30
	s_nop 0
	global_load_lds_dwordx4 v[132:133], off
	v_lshl_add_u64 v[132:133], v[0:1], 0, s[64:65]
	s_mov_b32 m0, s31
	s_nop 0
	global_load_lds_dwordx4 v[132:133], off
	v_lshl_add_u64 v[132:133], v[0:1], 0, s[66:67]
	s_mov_b32 m0, s48
	s_nop 0
	global_load_lds_dwordx4 v[132:133], off
	v_lshl_add_u64 v[132:133], v[0:1], 0, vcc
	s_mov_b32 m0, s49
	s_nop 0
	global_load_lds_dwordx4 v[132:133], off
	v_lshl_add_u64 v[132:133], v[0:1], 0, s[68:69]
	s_mov_b32 m0, s50
	s_nop 0
	global_load_lds_dwordx4 v[132:133], off
	ds_read_b128 v[132:135], v4
	ds_read_b128 v[136:139], v4 offset:2048
	ds_read_b128 v[140:143], v4 offset:4096
	ds_read_b128 v[144:147], v4 offset:6144
	ds_read_b128 v[148:151], v5
	ds_read_b128 v[152:155], v5 offset:2048
	ds_read_b128 v[180:183], v5 offset:4096
	ds_read_b128 v[184:187], v5 offset:6144
	ds_read_b128 v[188:191], v6
	ds_read_b128 v[192:195], v6 offset:2048
	ds_read_b128 v[196:199], v6 offset:4096
	ds_read_b128 v[200:203], v6 offset:6144
	ds_read_b128 v[204:207], v7
	ds_read_b128 v[208:211], v7 offset:2048
	ds_read_b128 v[212:215], v7 offset:4096
	ds_read_b128 v[216:219], v7 offset:6144
	s_waitcnt lgkmcnt(8)
	s_setprio 1
	v_mfma_f32_16x16x32_bf16 v[36:39], v[132:135], v[148:151], v[36:39]
	v_mfma_f32_16x16x32_bf16 v[56:59], v[132:135], v[152:155], v[56:59]
	v_mfma_f32_16x16x32_bf16 v[60:63], v[132:135], v[180:183], v[60:63]
	v_mfma_f32_16x16x32_bf16 v[8:11], v[132:135], v[184:187], v[8:11]
	v_mfma_f32_16x16x32_bf16 v[40:43], v[136:139], v[148:151], v[40:43]
	v_mfma_f32_16x16x32_bf16 v[48:51], v[136:139], v[152:155], v[48:51]
	v_mfma_f32_16x16x32_bf16 v[12:15], v[136:139], v[184:187], v[12:15]
	v_mfma_f32_16x16x32_bf16 v[44:47], v[140:143], v[148:151], v[44:47]
	v_mfma_f32_16x16x32_bf16 v[52:55], v[140:143], v[152:155], v[52:55]
	v_mfma_f32_16x16x32_bf16 v[16:19], v[140:143], v[184:187], v[16:19]
	v_mfma_f32_16x16x32_bf16 v[24:27], v[144:147], v[148:151], v[24:27]
	v_mfma_f32_16x16x32_bf16 v[28:31], v[144:147], v[152:155], v[28:31]
	v_mfma_f32_16x16x32_bf16 v[32:35], v[144:147], v[180:183], v[32:35]
	v_mfma_f32_16x16x32_bf16 v[20:23], v[144:147], v[184:187], v[20:23]
	v_mfma_f32_16x16x32_bf16 v[120:123], v[136:139], v[180:183], v[120:123]
	v_mfma_f32_16x16x32_bf16 v[124:127], v[140:143], v[180:183], v[124:127]
	s_waitcnt lgkmcnt(0)
	v_mfma_f32_16x16x32_bf16 v[36:39], v[188:191], v[204:207], v[36:39]
	v_mfma_f32_16x16x32_bf16 v[56:59], v[188:191], v[208:211], v[56:59]
	v_mfma_f32_16x16x32_bf16 v[60:63], v[188:191], v[212:215], v[60:63]
	v_mfma_f32_16x16x32_bf16 v[8:11], v[188:191], v[216:219], v[8:11]
	v_mfma_f32_16x16x32_bf16 v[40:43], v[192:195], v[204:207], v[40:43]
	v_mfma_f32_16x16x32_bf16 v[48:51], v[192:195], v[208:211], v[48:51]
	v_mfma_f32_16x16x32_bf16 v[12:15], v[192:195], v[216:219], v[12:15]
	v_mfma_f32_16x16x32_bf16 v[44:47], v[196:199], v[204:207], v[44:47]
	v_mfma_f32_16x16x32_bf16 v[52:55], v[196:199], v[208:211], v[52:55]
	v_mfma_f32_16x16x32_bf16 v[16:19], v[196:199], v[216:219], v[16:19]
	v_mfma_f32_16x16x32_bf16 v[24:27], v[200:203], v[204:207], v[24:27]
	v_mfma_f32_16x16x32_bf16 v[28:31], v[200:203], v[208:211], v[28:31]
	v_mfma_f32_16x16x32_bf16 v[32:35], v[200:203], v[212:215], v[32:35]
	v_mfma_f32_16x16x32_bf16 v[20:23], v[200:203], v[216:219], v[20:23]
	v_mfma_f32_16x16x32_bf16 v[120:123], v[192:195], v[212:215], v[120:123]
	v_mfma_f32_16x16x32_bf16 v[124:127], v[196:199], v[212:215], v[124:127]
	s_setprio 0
	s_mov_b64 s[64:65], 0x200
	s_mov_b32 m0, s53
	v_lshl_add_u64 v[132:133], v[2:3], 0, s[64:65]
	s_mov_b64 s[66:67], 0x8200
	s_waitcnt vmcnt(0)
	s_barrier
	global_load_lds_dwordx4 v[132:133], off
	v_lshl_add_u64 v[132:133], v[2:3], 0, s[66:67]
	s_mov_b32 m0, s51
	s_mov_b64 s[68:69], 0x10200
	global_load_lds_dwordx4 v[132:133], off
	v_lshl_add_u64 v[132:133], v[2:3], 0, s[68:69]
	s_mov_b32 m0, s52
	s_mov_b64 vcc, 0x18200
	global_load_lds_dwordx4 v[132:133], off
	v_lshl_add_u64 v[132:133], v[2:3], 0, vcc
	s_mov_b32 m0, s54
	s_nop 0
	global_load_lds_dwordx4 v[132:133], off
	v_lshl_add_u64 v[132:133], v[0:1], 0, s[64:65]
	s_mov_b32 m0, s55
	s_nop 0
	global_load_lds_dwordx4 v[132:133], off
	v_lshl_add_u64 v[132:133], v[0:1], 0, s[66:67]
	s_mov_b32 m0, s56
	s_nop 0
	global_load_lds_dwordx4 v[132:133], off
	v_lshl_add_u64 v[132:133], v[0:1], 0, s[68:69]
	s_mov_b32 m0, s57
	s_nop 0
	global_load_lds_dwordx4 v[132:133], off
	v_lshl_add_u64 v[132:133], v[0:1], 0, vcc
	s_mov_b32 m0, s58
	s_nop 0
	global_load_lds_dwordx4 v[132:133], off
	ds_read_b128 v[132:135], v111
	ds_read_b128 v[136:139], v111 offset:2048
	ds_read_b128 v[140:143], v111 offset:4096
	ds_read_b128 v[144:147], v111 offset:6144
	ds_read_b128 v[148:151], v113
	ds_read_b128 v[152:155], v113 offset:2048
	ds_read_b128 v[180:183], v113 offset:4096
	ds_read_b128 v[184:187], v113 offset:6144
	ds_read_b128 v[188:191], v115
	ds_read_b128 v[192:195], v115 offset:2048
	ds_read_b128 v[196:199], v115 offset:4096
	ds_read_b128 v[200:203], v115 offset:6144
	ds_read_b128 v[204:207], v117
	ds_read_b128 v[208:211], v117 offset:2048
	ds_read_b128 v[212:215], v117 offset:4096
	ds_read_b128 v[216:219], v117 offset:6144
	s_waitcnt lgkmcnt(8)
;     ...
;   for (int kt = 0; kt < nk; ++kt) {
;     asm volatile("s_waitcnt vmcnt(0)" ::: "memory");
;     __builtin_amdgcn_s_barrier();
;     if (kt + 1 < nk) stage(kt + 1, (kt + 1) & 1);
;     else if (chained && nbrow >= 0) {
;       const bfr* na = (nA ? nA : A) + (long)(nbrow + r0) * lda + cg;
;       const bfr* nb = (nBt ? nBt : Bt) + (long)(nbcol + r0) * ldb + cg;
; #pragma unroll
;       for (int i = 0; i < 4; ++i)
;         __builtin_amdgcn_global_load_lds((const unsigned*)(na + i * a32), (unsigned*)(smem + tid * 16 + i * 4096), 16, 0, 0);
; #pragma unroll
;       for (int i = 0; i < NF; ++i)
;         __builtin_amdgcn_global_load_lds((const unsigned*)(nb + i * b32), (unsigned*)(smem + 16384 + tid * 16 + i * 4096), 16, 0, 0);
;     }
;     const unsigned bo = (kt & 1) * 32768;
;     bf16x8 af[2][4], bfg[2][4];
;     if (NF == 4) {
;       asm volatile(
;           "ds_read_b128 %0, %16\n\tds_read_b128 %1, %16 offset:2048\n\tds_read_b128 %2, %16 offset:4096\n\tds_read_b128 %3, %16 offset:6144\n\t"
;           "ds_read_b128 %4, %17\n\tds_read_b128 %5, %17 offset:2048\n\tds_read_b128 %6, %17 offset:4096\n\tds_read_b128 %7, %17 offset:6144\n\t"
;           "ds_read_b128 %8, %18\n\tds_read_b128 %9, %18 offset:2048\n\tds_read_b128 %10, %18 offset:4096\n\tds_read_b128 %11, %18 offset:6144\n\t"
;           "ds_read_b128 %12, %19\n\tds_read_b128 %13, %19 offset:2048\n\tds_read_b128 %14, %19 offset:4096\n\tds_read_b128 %15, %19 offset:6144\n\t"
;           "s_waitcnt lgkmcnt(0)"
;           : "=&v"(af[0][0]), "=&v"(af[0][1]), "=&v"(af[0][2]), "=&v"(af[0][3]), "=&v"(bfg[0][0]), "=&v"(bfg[0][1]), "=&v"(bfg[0][2]), "=&v"(bfg[0][3]),
;             "=&v"(af[1][0]), "=&v"(af[1][1]), "=&v"(af[1][2]), "=&v"(af[1][3]), "=&v"(bfg[1][0]), "=&v"(bfg[1][1]), "=&v"(bfg[1][2]), "=&v"(bfg[1][3])
;           : "v"(arow + sw0 + bo), "v"(brw + sw0 + bo), "v"(arow + sw1 + bo), "v"(brw + sw1 + bo)
;           : "memory");
;     } else {
;       asm volatile(
;           "ds_read_b128 %0, %12\n\tds_read_b128 %1, %12 offset:2048\n\tds_read_b128 %2, %12 offset:4096\n\tds_read_b128 %3, %12 offset:6144\n\t"
;           "ds_read_b128 %4, %13\n\tds_read_b128 %5, %13 offset:2048\n\t"
;           "ds_read_b128 %6, %14\n\tds_read_b128 %7, %14 offset:2048\n\tds_read_b128 %8, %14 offset:4096\n\tds_read_b128 %9, %14 offset:6144\n\t"
	s_setprio 1
	v_mfma_f32_16x16x32_bf16 v[36:39], v[132:135], v[148:151], v[36:39]
	v_mfma_f32_16x16x32_bf16 v[56:59], v[132:135], v[152:155], v[56:59]
	v_mfma_f32_16x16x32_bf16 v[60:63], v[132:135], v[180:183], v[60:63]
	v_mfma_f32_16x16x32_bf16 v[8:11], v[132:135], v[184:187], v[8:11]
	v_mfma_f32_16x16x32_bf16 v[40:43], v[136:139], v[148:151], v[40:43]
	v_mfma_f32_16x16x32_bf16 v[48:51], v[136:139], v[152:155], v[48:51]
	v_mfma_f32_16x16x32_bf16 v[12:15], v[136:139], v[184:187], v[12:15]
	v_mfma_f32_16x16x32_bf16 v[44:47], v[140:143], v[148:151], v[44:47]
	v_mfma_f32_16x16x32_bf16 v[52:55], v[140:143], v[152:155], v[52:55]
	v_mfma_f32_16x16x32_bf16 v[16:19], v[140:143], v[184:187], v[16:19]
	v_mfma_f32_16x16x32_bf16 v[24:27], v[144:147], v[148:151], v[24:27]
	v_mfma_f32_16x16x32_bf16 v[28:31], v[144:147], v[152:155], v[28:31]
	v_mfma_f32_16x16x32_bf16 v[32:35], v[144:147], v[180:183], v[32:35]
	v_mfma_f32_16x16x32_bf16 v[20:23], v[144:147], v[184:187], v[20:23]
	v_mfma_f32_16x16x32_bf16 v[120:123], v[136:139], v[180:183], v[120:123]
	v_mfma_f32_16x16x32_bf16 v[124:127], v[140:143], v[180:183], v[124:127]
	s_waitcnt lgkmcnt(0)
	v_mfma_f32_16x16x32_bf16 v[36:39], v[188:191], v[204:207], v[36:39]
	v_mfma_f32_16x16x32_bf16 v[56:59], v[188:191], v[208:211], v[56:59]
	v_mfma_f32_16x16x32_bf16 v[60:63], v[188:191], v[212:215], v[60:63]
	v_mfma_f32_16x16x32_bf16 v[8:11], v[188:191], v[216:219], v[8:11]
	v_mfma_f32_16x16x32_bf16 v[40:43], v[192:195], v[204:207], v[40:43]
	v_mfma_f32_16x16x32_bf16 v[48:51], v[192:195], v[208:211], v[48:51]
	v_mfma_f32_16x16x32_bf16 v[12:15], v[192:195], v[216:219], v[12:15]
	v_mfma_f32_16x16x32_bf16 v[44:47], v[196:199], v[204:207], v[44:47]
	v_mfma_f32_16x16x32_bf16 v[52:55], v[196:199], v[208:211], v[52:55]
	v_mfma_f32_16x16x32_bf16 v[16:19], v[196:199], v[216:219], v[16:19]
	v_mfma_f32_16x16x32_bf16 v[24:27], v[200:203], v[204:207], v[24:27]
	v_mfma_f32_16x16x32_bf16 v[28:31], v[200:203], v[208:211], v[28:31]
	v_mfma_f32_16x16x32_bf16 v[32:35], v[200:203], v[212:215], v[32:35]
	v_mfma_f32_16x16x32_bf16 v[20:23], v[200:203], v[216:219], v[20:23]
	v_mfma_f32_16x16x32_bf16 v[120:123], v[192:195], v[212:215], v[120:123]
	v_mfma_f32_16x16x32_bf16 v[124:127], v[196:199], v[212:215], v[124:127]
	s_setprio 0
	s_mov_b64 s[64:65], 0x280
	s_mov_b32 m0, s29
	v_lshl_add_u64 v[132:133], v[2:3], 0, s[64:65]
	s_mov_b64 s[66:67], 0x8280
	s_waitcnt vmcnt(0)
	s_barrier
	global_load_lds_dwordx4 v[132:133], off
	v_lshl_add_u64 v[132:133], v[2:3], 0, s[66:67]
	s_mov_b32 m0, s27
	s_mov_b64 s[68:69], 0x10280
	global_load_lds_dwordx4 v[132:133], off
	v_lshl_add_u64 v[132:133], v[2:3], 0, s[68:69]
	s_mov_b32 m0, s28
	s_mov_b64 vcc, 0x18280
	global_load_lds_dwordx4 v[132:133], off
	v_lshl_add_u64 v[132:133], v[2:3], 0, vcc
	s_mov_b32 m0, s30
	s_nop 0
	global_load_lds_dwordx4 v[132:133], off
	v_lshl_add_u64 v[132:133], v[0:1], 0, s[64:65]
	s_mov_b32 m0, s31
	s_nop 0
	global_load_lds_dwordx4 v[132:133], off
	v_lshl_add_u64 v[132:133], v[0:1], 0, s[66:67]
	s_mov_b32 m0, s48
	s_nop 0
	global_load_lds_dwordx4 v[132:133], off
	v_lshl_add_u64 v[132:133], v[0:1], 0, s[68:69]
	s_mov_b32 m0, s49
	s_nop 0
	global_load_lds_dwordx4 v[132:133], off
	v_lshl_add_u64 v[132:133], v[0:1], 0, vcc
	s_mov_b32 m0, s50
	s_nop 0
	global_load_lds_dwordx4 v[132:133], off
	ds_read_b128 v[132:135], v4
	ds_read_b128 v[136:139], v4 offset:2048
	ds_read_b128 v[140:143], v4 offset:4096
	ds_read_b128 v[144:147], v4 offset:6144
	ds_read_b128 v[148:151], v5
	ds_read_b128 v[152:155], v5 offset:2048
	ds_read_b128 v[180:183], v5 offset:4096
	ds_read_b128 v[184:187], v5 offset:6144
	ds_read_b128 v[188:191], v6
	ds_read_b128 v[192:195], v6 offset:2048
	ds_read_b128 v[196:199], v6 offset:4096
	ds_read_b128 v[200:203], v6 offset:6144
	ds_read_b128 v[204:207], v7
	ds_read_b128 v[208:211], v7 offset:2048
	ds_read_b128 v[212:215], v7 offset:4096
	ds_read_b128 v[216:219], v7 offset:6144
	s_waitcnt lgkmcnt(8)
	s_setprio 1
	v_mfma_f32_16x16x32_bf16 v[36:39], v[132:135], v[148:151], v[36:39]
	v_mfma_f32_16x16x32_bf16 v[56:59], v[132:135], v[152:155], v[56:59]
	v_mfma_f32_16x16x32_bf16 v[60:63], v[132:135], v[180:183], v[60:63]
	v_mfma_f32_16x16x32_bf16 v[8:11], v[132:135], v[184:187], v[8:11]
	v_mfma_f32_16x16x32_bf16 v[40:43], v[136:139], v[148:151], v[40:43]
	v_mfma_f32_16x16x32_bf16 v[48:51], v[136:139], v[152:155], v[48:51]
	v_mfma_f32_16x16x32_bf16 v[12:15], v[136:139], v[184:187], v[12:15]
	v_mfma_f32_16x16x32_bf16 v[44:47], v[140:143], v[148:151], v[44:47]
	v_mfma_f32_16x16x32_bf16 v[52:55], v[140:143], v[152:155], v[52:55]
	v_mfma_f32_16x16x32_bf16 v[16:19], v[140:143], v[184:187], v[16:19]
	v_mfma_f32_16x16x32_bf16 v[24:27], v[144:147], v[148:151], v[24:27]
	v_mfma_f32_16x16x32_bf16 v[28:31], v[144:147], v[152:155], v[28:31]
	v_mfma_f32_16x16x32_bf16 v[32:35], v[144:147], v[180:183], v[32:35]
	v_mfma_f32_16x16x32_bf16 v[20:23], v[144:147], v[184:187], v[20:23]
	v_mfma_f32_16x16x32_bf16 v[120:123], v[136:139], v[180:183], v[120:123]
	v_mfma_f32_16x16x32_bf16 v[124:127], v[140:143], v[180:183], v[124:127]
	s_waitcnt lgkmcnt(0)
	v_mfma_f32_16x16x32_bf16 v[36:39], v[188:191], v[204:207], v[36:39]
	v_mfma_f32_16x16x32_bf16 v[56:59], v[188:191], v[208:211], v[56:59]
	v_mfma_f32_16x16x32_bf16 v[60:63], v[188:191], v[212:215], v[60:63]
	v_mfma_f32_16x16x32_bf16 v[8:11], v[188:191], v[216:219], v[8:11]
	v_mfma_f32_16x16x32_bf16 v[40:43], v[192:195], v[204:207], v[40:43]
	v_mfma_f32_16x16x32_bf16 v[48:51], v[192:195], v[208:211], v[48:51]
	v_mfma_f32_16x16x32_bf16 v[12:15], v[192:195], v[216:219], v[12:15]
	v_mfma_f32_16x16x32_bf16 v[44:47], v[196:199], v[204:207], v[44:47]
	v_mfma_f32_16x16x32_bf16 v[52:55], v[196:199], v[208:211], v[52:55]
	v_mfma_f32_16x16x32_bf16 v[16:19], v[196:199], v[216:219], v[16:19]
	v_mfma_f32_16x16x32_bf16 v[24:27], v[200:203], v[204:207], v[24:27]
	v_mfma_f32_16x16x32_bf16 v[28:31], v[200:203], v[208:211], v[28:31]
	v_mfma_f32_16x16x32_bf16 v[32:35], v[200:203], v[212:215], v[32:35]
	v_mfma_f32_16x16x32_bf16 v[20:23], v[200:203], v[216:219], v[20:23]
	v_mfma_f32_16x16x32_bf16 v[120:123], v[192:195], v[212:215], v[120:123]
	v_mfma_f32_16x16x32_bf16 v[124:127], v[196:199], v[212:215], v[124:127]
	s_setprio 0
	s_mov_b64 s[64:65], 0x300
	s_mov_b32 m0, s53
	v_lshl_add_u64 v[132:133], v[2:3], 0, s[64:65]
	s_mov_b64 s[66:67], 0x8300
	s_waitcnt vmcnt(0)
	s_barrier
;     ...
;   for (int kt = 0; kt < nk; ++kt) {
;     asm volatile("s_waitcnt vmcnt(0)" ::: "memory");
;     __builtin_amdgcn_s_barrier();
;     if (kt + 1 < nk) stage(kt + 1, (kt + 1) & 1);
;     else if (chained && nbrow >= 0) {
;       const bfr* na = (nA ? nA : A) + (long)(nbrow + r0) * lda + cg;
;       const bfr* nb = (nBt ? nBt : Bt) + (long)(nbcol + r0) * ldb + cg;
; #pragma unroll
;       for (int i = 0; i < 4; ++i)
;         __builtin_amdgcn_global_load_lds((const unsigned*)(na + i * a32), (unsigned*)(smem + tid * 16 + i * 4096), 16, 0, 0);
; #pragma unroll
;       for (int i = 0; i < NF; ++i)
;         __builtin_amdgcn_global_load_lds((const unsigned*)(nb + i * b32), (unsigned*)(smem + 16384 + tid * 16 + i * 4096), 16, 0, 0);
;     }
;     const unsigned bo = (kt & 1) * 32768;
;     bf16x8 af[2][4], bfg[2][4];
;     if (NF == 4) {
;       asm volatile(
;           "ds_read_b128 %0, %16\n\tds_read_b128 %1, %16 offset:2048\n\tds_read_b128 %2, %16 offset:4096\n\tds_read_b128 %3, %16 offset:6144\n\t"
;           "ds_read_b128 %4, %17\n\tds_read_b128 %5, %17 offset:2048\n\tds_read_b128 %6, %17 offset:4096\n\tds_read_b128 %7, %17 offset:6144\n\t"
;           "ds_read_b128 %8, %18\n\tds_read_b128 %9, %18 offset:2048\n\tds_read_b128 %10, %18 offset:4096\n\tds_read_b128 %11, %18 offset:6144\n\t"
;           "ds_read_b128 %12, %19\n\tds_read_b128 %13, %19 offset:2048\n\tds_read_b128 %14, %19 offset:4096\n\tds_read_b128 %15, %19 offset:6144\n\t"
;           "s_waitcnt lgkmcnt(0)"
;           : "=&v"(af[0][0]), "=&v"(af[0][1]), "=&v"(af[0][2]), "=&v"(af[0][3]), "=&v"(bfg[0][0]), "=&v"(bfg[0][1]), "=&v"(bfg[0][2]), "=&v"(bfg[0][3]),
;             "=&v"(af[1][0]), "=&v"(af[1][1]), "=&v"(af[1][2]), "=&v"(af[1][3]), "=&v"(bfg[1][0]), "=&v"(bfg[1][1]), "=&v"(bfg[1][2]), "=&v"(bfg[1][3])
;           : "v"(arow + sw0 + bo), "v"(brw + sw0 + bo), "v"(arow + sw1 + bo), "v"(brw + sw1 + bo)
;           : "memory");
;     } else {
;       asm volatile(
;           "ds_read_b128 %0, %12\n\tds_read_b128 %1, %12 offset:2048\n\tds_read_b128 %2, %12 offset:4096\n\tds_read_b128 %3, %12 offset:6144\n\t"
;           "ds_read_b128 %4, %13\n\tds_read_b128 %5, %13 offset:2048\n\t"
;           "ds_read_b128 %6, %14\n\tds_read_b128 %7, %14 offset:2048\n\tds_read_b128 %8, %14 offset:4096\n\tds_read_b128 %9, %14 offset:6144\n\t"
	global_load_lds_dwordx4 v[132:133], off
	v_lshl_add_u64 v[132:133], v[2:3], 0, s[66:67]
	s_mov_b32 m0, s51
	s_mov_b64 s[68:69], 0x10300
	global_load_lds_dwordx4 v[132:133], off
	v_lshl_add_u64 v[132:133], v[2:3], 0, s[68:69]
	s_mov_b32 m0, s52
	s_mov_b64 s[52:53], 0x18300
	global_load_lds_dwordx4 v[132:133], off
	v_lshl_add_u64 v[132:133], v[2:3], 0, s[52:53]
	s_mov_b32 m0, s54
	s_nop 0
	global_load_lds_dwordx4 v[132:133], off
	v_lshl_add_u64 v[132:133], v[0:1], 0, s[64:65]
	s_mov_b32 m0, s55
	s_nop 0
	global_load_lds_dwordx4 v[132:133], off
	v_lshl_add_u64 v[132:133], v[0:1], 0, s[66:67]
	s_mov_b32 m0, s56
	s_nop 0
	global_load_lds_dwordx4 v[132:133], off
	v_lshl_add_u64 v[132:133], v[0:1], 0, s[68:69]
	s_mov_b32 m0, s57
	s_nop 0
	global_load_lds_dwordx4 v[132:133], off
	v_lshl_add_u64 v[132:133], v[0:1], 0, s[52:53]
	s_mov_b32 m0, s58
	s_nop 0
	global_load_lds_dwordx4 v[132:133], off
	ds_read_b128 v[132:135], v111
	ds_read_b128 v[136:139], v111 offset:2048
	ds_read_b128 v[140:143], v111 offset:4096
	ds_read_b128 v[144:147], v111 offset:6144
	ds_read_b128 v[148:151], v113
	ds_read_b128 v[152:155], v113 offset:2048
	ds_read_b128 v[180:183], v113 offset:4096
	ds_read_b128 v[184:187], v113 offset:6144
	ds_read_b128 v[188:191], v115
	ds_read_b128 v[192:195], v115 offset:2048
	ds_read_b128 v[196:199], v115 offset:4096
	ds_read_b128 v[200:203], v115 offset:6144
	ds_read_b128 v[204:207], v117
	ds_read_b128 v[208:211], v117 offset:2048
	ds_read_b128 v[212:215], v117 offset:4096
	ds_read_b128 v[216:219], v117 offset:6144
	s_waitcnt lgkmcnt(8)
	s_setprio 1
	v_mfma_f32_16x16x32_bf16 v[36:39], v[132:135], v[148:151], v[36:39]
	v_mfma_f32_16x16x32_bf16 v[56:59], v[132:135], v[152:155], v[56:59]
	v_mfma_f32_16x16x32_bf16 v[60:63], v[132:135], v[180:183], v[60:63]
	v_mfma_f32_16x16x32_bf16 v[8:11], v[132:135], v[184:187], v[8:11]
	v_mfma_f32_16x16x32_bf16 v[40:43], v[136:139], v[148:151], v[40:43]
	v_mfma_f32_16x16x32_bf16 v[48:51], v[136:139], v[152:155], v[48:51]
	v_mfma_f32_16x16x32_bf16 v[12:15], v[136:139], v[184:187], v[12:15]
	v_mfma_f32_16x16x32_bf16 v[44:47], v[140:143], v[148:151], v[44:47]
	v_mfma_f32_16x16x32_bf16 v[52:55], v[140:143], v[152:155], v[52:55]
	v_mfma_f32_16x16x32_bf16 v[16:19], v[140:143], v[184:187], v[16:19]
	v_mfma_f32_16x16x32_bf16 v[24:27], v[144:147], v[148:151], v[24:27]
	v_mfma_f32_16x16x32_bf16 v[28:31], v[144:147], v[152:155], v[28:31]
	v_mfma_f32_16x16x32_bf16 v[32:35], v[144:147], v[180:183], v[32:35]
	v_mfma_f32_16x16x32_bf16 v[20:23], v[144:147], v[184:187], v[20:23]
	v_mfma_f32_16x16x32_bf16 v[120:123], v[136:139], v[180:183], v[120:123]
	v_mfma_f32_16x16x32_bf16 v[124:127], v[140:143], v[180:183], v[124:127]
	s_waitcnt lgkmcnt(0)
	v_mfma_f32_16x16x32_bf16 v[36:39], v[188:191], v[204:207], v[36:39]
	v_mfma_f32_16x16x32_bf16 v[56:59], v[188:191], v[208:211], v[56:59]
	v_mfma_f32_16x16x32_bf16 v[60:63], v[188:191], v[212:215], v[60:63]
	v_mfma_f32_16x16x32_bf16 v[8:11], v[188:191], v[216:219], v[8:11]
	v_mfma_f32_16x16x32_bf16 v[40:43], v[192:195], v[204:207], v[40:43]
	v_mfma_f32_16x16x32_bf16 v[48:51], v[192:195], v[208:211], v[48:51]
	v_mfma_f32_16x16x32_bf16 v[12:15], v[192:195], v[216:219], v[12:15]
	v_mfma_f32_16x16x32_bf16 v[44:47], v[196:199], v[204:207], v[44:47]
	v_mfma_f32_16x16x32_bf16 v[52:55], v[196:199], v[208:211], v[52:55]
	v_mfma_f32_16x16x32_bf16 v[16:19], v[196:199], v[216:219], v[16:19]
	v_mfma_f32_16x16x32_bf16 v[24:27], v[200:203], v[204:207], v[24:27]
	v_mfma_f32_16x16x32_bf16 v[28:31], v[200:203], v[208:211], v[28:31]
	v_mfma_f32_16x16x32_bf16 v[32:35], v[200:203], v[212:215], v[32:35]
	v_mfma_f32_16x16x32_bf16 v[20:23], v[200:203], v[216:219], v[20:23]
	v_mfma_f32_16x16x32_bf16 v[120:123], v[192:195], v[212:215], v[120:123]
	v_mfma_f32_16x16x32_bf16 v[124:127], v[196:199], v[212:215], v[124:127]
	s_setprio 0
	s_mov_b64 s[52:53], 0x380
	s_mov_b32 m0, s29
	v_lshl_add_u64 v[132:133], v[2:3], 0, s[52:53]
	s_mov_b64 s[54:55], 0x8380
	s_waitcnt vmcnt(0)
	s_barrier
	global_load_lds_dwordx4 v[132:133], off
	v_lshl_add_u64 v[132:133], v[2:3], 0, s[54:55]
	s_mov_b32 m0, s27
	s_mov_b64 s[56:57], 0x10380
	global_load_lds_dwordx4 v[132:133], off
	v_lshl_add_u64 v[132:133], v[2:3], 0, s[56:57]
	s_mov_b32 m0, s28
	s_mov_b64 s[28:29], 0x18380
	global_load_lds_dwordx4 v[132:133], off
	v_lshl_add_u64 v[2:3], v[2:3], 0, s[28:29]
	s_mov_b32 m0, s30
	s_nop 0
	global_load_lds_dwordx4 v[2:3], off
	v_lshl_add_u64 v[2:3], v[0:1], 0, s[52:53]
	s_mov_b32 m0, s31
	s_nop 0
	global_load_lds_dwordx4 v[2:3], off
	v_lshl_add_u64 v[2:3], v[0:1], 0, s[54:55]
	s_mov_b32 m0, s48
	s_nop 0
	global_load_lds_dwordx4 v[2:3], off
	v_lshl_add_u64 v[2:3], v[0:1], 0, s[56:57]
	s_mov_b32 m0, s49
	v_lshl_add_u64 v[0:1], v[0:1], 0, s[28:29]
	global_load_lds_dwordx4 v[2:3], off
	s_mov_b32 m0, s50
	s_nop 0
	global_load_lds_dwordx4 v[0:1], off
	ds_read_b128 v[0:3], v4
	ds_read_b128 v[132:135], v4 offset:2048
	ds_read_b128 v[136:139], v4 offset:4096
	ds_read_b128 v[140:143], v4 offset:6144
	ds_read_b128 v[144:147], v5
	ds_read_b128 v[148:151], v5 offset:2048
	ds_read_b128 v[152:155], v5 offset:4096
	ds_read_b128 v[180:183], v5 offset:6144
	ds_read_b128 v[184:187], v6
	ds_read_b128 v[188:191], v6 offset:2048
	ds_read_b128 v[192:195], v6 offset:4096
	ds_read_b128 v[196:199], v6 offset:6144
	ds_read_b128 v[200:203], v7
	ds_read_b128 v[204:207], v7 offset:2048
	ds_read_b128 v[208:211], v7 offset:4096
	ds_read_b128 v[212:215], v7 offset:6144
	s_waitcnt lgkmcnt(8)
;     ...
;   for (int kt = 0; kt < nk; ++kt) {
;     asm volatile("s_waitcnt vmcnt(0)" ::: "memory");
;     __builtin_amdgcn_s_barrier();
;     if (kt + 1 < nk) stage(kt + 1, (kt + 1) & 1);
;     else if (chained && nbrow >= 0) {
;       const bfr* na = (nA ? nA : A) + (long)(nbrow + r0) * lda + cg;
;       const bfr* nb = (nBt ? nBt : Bt) + (long)(nbcol + r0) * ldb + cg;
; #pragma unroll
;       for (int i = 0; i < 4; ++i)
;         __builtin_amdgcn_global_load_lds((const unsigned*)(na + i * a32), (unsigned*)(smem + tid * 16 + i * 4096), 16, 0, 0);
; #pragma unroll
;       for (int i = 0; i < NF; ++i)
;         __builtin_amdgcn_global_load_lds((const unsigned*)(nb + i * b32), (unsigned*)(smem + 16384 + tid * 16 + i * 4096), 16, 0, 0);
;     }
;     const unsigned bo = (kt & 1) * 32768;
;     bf16x8 af[2][4], bfg[2][4];
;     if (NF == 4) {
;       asm volatile(
;           "ds_read_b128 %0, %16\n\tds_read_b128 %1, %16 offset:2048\n\tds_read_b128 %2, %16 offset:4096\n\tds_read_b128 %3, %16 offset:6144\n\t"
;           "ds_read_b128 %4, %17\n\tds_read_b128 %5, %17 offset:2048\n\tds_read_b128 %6, %17 offset:4096\n\tds_read_b128 %7, %17 offset:6144\n\t"
;           "ds_read_b128 %8, %18\n\tds_read_b128 %9, %18 offset:2048\n\tds_read_b128 %10, %18 offset:4096\n\tds_read_b128 %11, %18 offset:6144\n\t"
;           "ds_read_b128 %12, %19\n\tds_read_b128 %13, %19 offset:2048\n\tds_read_b128 %14, %19 offset:4096\n\tds_read_b128 %15, %19 offset:6144\n\t"
;           "s_waitcnt lgkmcnt(0)"
;           : "=&v"(af[0][0]), "=&v"(af[0][1]), "=&v"(af[0][2]), "=&v"(af[0][3]), "=&v"(bfg[0][0]), "=&v"(bfg[0][1]), "=&v"(bfg[0][2]), "=&v"(bfg[0][3]),
;             "=&v"(af[1][0]), "=&v"(af[1][1]), "=&v"(af[1][2]), "=&v"(af[1][3]), "=&v"(bfg[1][0]), "=&v"(bfg[1][1]), "=&v"(bfg[1][2]), "=&v"(bfg[1][3])
;           : "v"(arow + sw0 + bo), "v"(brw + sw0 + bo), "v"(arow + sw1 + bo), "v"(brw + sw1 + bo)
;           : "memory");
;     } else {
;       asm volatile(
;           "ds_read_b128 %0, %12\n\tds_read_b128 %1, %12 offset:2048\n\tds_read_b128 %2, %12 offset:4096\n\tds_read_b128 %3, %12 offset:6144\n\t"
;           "ds_read_b128 %4, %13\n\tds_read_b128 %5, %13 offset:2048\n\t"
;           "ds_read_b128 %6, %14\n\tds_read_b128 %7, %14 offset:2048\n\tds_read_b128 %8, %14 offset:4096\n\tds_read_b128 %9, %14 offset:6144\n\t"
	s_setprio 1
	v_mfma_f32_16x16x32_bf16 v[4:7], v[0:3], v[144:147], v[36:39]
	v_mfma_f32_16x16x32_bf16 v[36:39], v[0:3], v[148:151], v[56:59]
	v_mfma_f32_16x16x32_bf16 v[56:59], v[0:3], v[152:155], v[60:63]
	v_mfma_f32_16x16x32_bf16 v[60:63], v[0:3], v[180:183], v[8:11]
	v_mfma_f32_16x16x32_bf16 v[40:43], v[132:135], v[144:147], v[40:43]
	v_mfma_f32_16x16x32_bf16 v[48:51], v[132:135], v[148:151], v[48:51]
	v_mfma_f32_16x16x32_bf16 v[120:123], v[132:135], v[152:155], v[120:123]
	v_mfma_f32_16x16x32_bf16 v[132:135], v[132:135], v[180:183], v[12:15]
	v_mfma_f32_16x16x32_bf16 v[44:47], v[136:139], v[144:147], v[44:47]
	v_mfma_f32_16x16x32_bf16 v[52:55], v[136:139], v[148:151], v[52:55]
	v_mfma_f32_16x16x32_bf16 v[124:127], v[136:139], v[152:155], v[124:127]
	v_mfma_f32_16x16x32_bf16 v[136:139], v[136:139], v[180:183], v[16:19]
	v_mfma_f32_16x16x32_bf16 v[144:147], v[140:143], v[144:147], v[24:27]
	v_mfma_f32_16x16x32_bf16 v[148:151], v[140:143], v[148:151], v[28:31]
	v_mfma_f32_16x16x32_bf16 v[152:155], v[140:143], v[152:155], v[32:35]
	v_mfma_f32_16x16x32_bf16 v[140:143], v[140:143], v[180:183], v[20:23]
	s_waitcnt lgkmcnt(0)
	v_mfma_f32_16x16x32_bf16 v[0:3], v[184:187], v[200:203], v[4:7]
	v_mfma_f32_16x16x32_bf16 v[4:7], v[184:187], v[204:207], v[36:39]
	v_mfma_f32_16x16x32_bf16 v[8:11], v[184:187], v[208:211], v[56:59]
	v_mfma_f32_16x16x32_bf16 v[12:15], v[184:187], v[212:215], v[60:63]
	v_mfma_f32_16x16x32_bf16 v[16:19], v[188:191], v[200:203], v[40:43]
	v_mfma_f32_16x16x32_bf16 v[20:23], v[188:191], v[204:207], v[48:51]
	v_mfma_f32_16x16x32_bf16 v[24:27], v[188:191], v[208:211], v[120:123]
	v_mfma_f32_16x16x32_bf16 v[28:31], v[188:191], v[212:215], v[132:135]
	v_mfma_f32_16x16x32_bf16 v[32:35], v[192:195], v[200:203], v[44:47]
	v_mfma_f32_16x16x32_bf16 v[36:39], v[192:195], v[204:207], v[52:55]
	v_mfma_f32_16x16x32_bf16 v[40:43], v[192:195], v[208:211], v[124:127]
	v_mfma_f32_16x16x32_bf16 v[44:47], v[192:195], v[212:215], v[136:139]
	v_mfma_f32_16x16x32_bf16 v[48:51], v[196:199], v[200:203], v[144:147]
	v_mfma_f32_16x16x32_bf16 v[52:55], v[196:199], v[204:207], v[148:151]
	v_mfma_f32_16x16x32_bf16 v[56:59], v[196:199], v[208:211], v[152:155]
	v_mfma_f32_16x16x32_bf16 v[60:63], v[196:199], v[212:215], v[140:143]
	s_setprio 0
	s_waitcnt vmcnt(0)
	s_cmp_lt_i32 s26, 0
	s_barrier
	s_cbranch_scc1 .LBB0_4966
	s_and_b64 s[20:21], s[20:21], exec
	s_cselect_b32 s27, 0xed7cc00, s87
	s_and_b64 s[20:21], s[22:23], exec
	s_cselect_b32 s22, 0xcb3cc00, s27
	s_and_b64 s[20:21], s[24:25], exec
	s_cselect_b32 s20, 0, s47
	s_add_i32 s20, s20, s35
	s_ashr_i32 s21, s20, 31
	s_lshl_b64 s[20:21], s[20:21], 20
	s_add_u32 s20, s39, s20
	s_addc_u32 s21, s40, s21
	s_add_u32 s22, s10, s22
	s_addc_u32 s23, s11, 0
	s_and_b64 s[24:25], s[24:25], exec
	s_cselect_b32 s24, s45, s16
	v_add_u32_e32 v120, s24, v74
	v_add_u32_e32 v122, s26, v74
	v_ashrrev_i32_e32 v121, 31, v120
	v_ashrrev_i32_e32 v123, 31, v122
	v_lshlrev_b64 v[120:121], 10, v[120:121]
	v_lshlrev_b64 v[122:123], 10, v[122:123]
	v_lshl_add_u64 v[120:121], s[20:21], 0, v[120:121]
	v_lshl_add_u64 v[122:123], s[22:23], 0, v[122:123]
	v_readfirstlane_b32 s20, v75
	v_lshl_add_u64 v[122:123], v[122:123], 0, v[128:129]
	s_mov_b32 m0, s20
	s_mov_b64 s[22:23], 0x8000
	v_readfirstlane_b32 s20, v76
	global_load_lds_dwordx4 v[122:123], off
	v_lshl_add_u64 v[74:75], v[122:123], 0, s[22:23]
	s_mov_b32 m0, s20
	s_mov_b64 s[24:25], 0x10000
	v_readfirstlane_b32 s20, v77
	global_load_lds_dwordx4 v[74:75], off
	v_lshl_add_u64 v[74:75], v[122:123], 0, s[24:25]
	s_mov_b32 m0, s20
	s_mov_b64 s[26:27], 0x18000
	v_readfirstlane_b32 s20, v110
	global_load_lds_dwordx4 v[74:75], off
	v_lshl_add_u64 v[74:75], v[122:123], 0, s[26:27]
	s_mov_b32 m0, s20
	v_readfirstlane_b32 s20, v112
	v_lshl_add_u64 v[120:121], v[120:121], 0, v[128:129]
	global_load_lds_dwordx4 v[74:75], off
	s_mov_b32 m0, s20
	v_readfirstlane_b32 s20, v114
	global_load_lds_dwordx4 v[120:121], off
	v_lshl_add_u64 v[74:75], v[120:121], 0, s[22:23]
	s_mov_b32 m0, s20
	v_readfirstlane_b32 s20, v116
	global_load_lds_dwordx4 v[74:75], off
	v_lshl_add_u64 v[74:75], v[120:121], 0, s[24:25]
	s_mov_b32 m0, s20
	v_readfirstlane_b32 s20, v118
	global_load_lds_dwordx4 v[74:75], off
	v_lshl_add_u64 v[74:75], v[120:121], 0, s[26:27]
	s_mov_b32 m0, s20
	s_nop 0
	global_load_lds_dwordx4 v[74:75], off
;     ...
;     const unsigned bo = (kt & 1) * 32768;
;     bf16x8 af[2][4], bfg[2][4];
;     if (NF == 4) {
;       asm volatile(
;           "ds_read_b128 %0, %16\n\tds_read_b128 %1, %16 offset:2048\n\tds_read_b128 %2, %16 offset:4096\n\tds_read_b128 %3, %16 offset:6144\n\t"
;           "ds_read_b128 %4, %17\n\tds_read_b128 %5, %17 offset:2048\n\tds_read_b128 %6, %17 offset:4096\n\tds_read_b128 %7, %17 offset:6144\n\t"
;           "ds_read_b128 %8, %18\n\tds_read_b128 %9, %18 offset:2048\n\tds_read_b128 %10, %18 offset:4096\n\tds_read_b128 %11, %18 offset:6144\n\t"
;           "ds_read_b128 %12, %19\n\tds_read_b128 %13, %19 offset:2048\n\tds_read_b128 %14, %19 offset:4096\n\tds_read_b128 %15, %19 offset:6144\n\t"
;           "s_waitcnt lgkmcnt(0)"
;           : "=&v"(af[0][0]), "=&v"(af[0][1]), "=&v"(af[0][2]), "=&v"(af[0][3]), "=&v"(bfg[0][0]), "=&v"(bfg[0][1]), "=&v"(bfg[0][2]), "=&v"(bfg[0][3]),
;             "=&v"(af[1][0]), "=&v"(af[1][1]), "=&v"(af[1][2]), "=&v"(af[1][3]), "=&v"(bfg[1][0]), "=&v"(bfg[1][1]), "=&v"(bfg[1][2]), "=&v"(bfg[1][3])
;           : "v"(arow + sw0 + bo), "v"(brw + sw0 + bo), "v"(arow + sw1 + bo), "v"(brw + sw1 + bo)
;           : "memory");
;     } else {
;       asm volatile(
;           "ds_read_b128 %0, %12\n\tds_read_b128 %1, %12 offset:2048\n\tds_read_b128 %2, %12 offset:4096\n\tds_read_b128 %3, %12 offset:6144\n\t"
;           "ds_read_b128 %4, %13\n\tds_read_b128 %5, %13 offset:2048\n\t"
;           "ds_read_b128 %6, %14\n\tds_read_b128 %7, %14 offset:2048\n\tds_read_b128 %8, %14 offset:4096\n\tds_read_b128 %9, %14 offset:6144\n\t"
;           "ds_read_b128 %10, %15\n\tds_read_b128 %11, %15 offset:2048\n\t"
;           "s_waitcnt lgkmcnt(0)"
;           : "=&v"(af[0][0]), "=&v"(af[0][1]), "=&v"(af[0][2]), "=&v"(af[0][3]), "=&v"(bfg[0][0]), "=&v"(bfg[0][1]),
;             "=&v"(af[1][0]), "=&v"(af[1][1]), "=&v"(af[1][2]), "=&v"(af[1][3]), "=&v"(bfg[1][0]), "=&v"(bfg[1][1])
;           : "v"(arow + sw0 + bo), "v"(brw + sw0 + bo), "v"(arow + sw1 + bo), "v"(brw + sw1 + bo)
;           : "memory");
;     }
;     __builtin_amdgcn_s_setprio(1);
; #pragma unroll
;     for (int ks = 0; ks < 2; ++ks)
; #pragma unroll
;       for (int m = 0; m < 4; ++m)
; #pragma unroll
;         for (int n = 0; n < NF; ++n) acc[m][n] = MFMA16(af[ks][m], bfg[ks][n], acc[m][n]);
;     __builtin_amdgcn_s_setprio(0);
;   }
.LBB0_4966:
	ds_read_b128 v[74:77], v111
	ds_read_b128 v[118:121], v111 offset:2048
	ds_read_b128 v[122:125], v111 offset:4096
	ds_read_b128 v[132:135], v111 offset:6144
	ds_read_b128 v[136:139], v113
	ds_read_b128 v[140:143], v113 offset:2048
	ds_read_b128 v[144:147], v113 offset:4096
	ds_read_b128 v[148:151], v113 offset:6144
	ds_read_b128 v[152:155], v115
	ds_read_b128 v[180:183], v115 offset:2048
	ds_read_b128 v[184:187], v115 offset:4096
	ds_read_b128 v[188:191], v115 offset:6144
	ds_read_b128 v[192:195], v117
	ds_read_b128 v[196:199], v117 offset:2048
	ds_read_b128 v[200:203], v117 offset:4096
	ds_read_b128 v[204:207], v117 offset:6144
	s_waitcnt lgkmcnt(8)
	s_setprio 1
	v_mfma_f32_16x16x32_bf16 v[0:3], v[74:77], v[136:139], v[0:3]
	v_mfma_f32_16x16x32_bf16 v[4:7], v[74:77], v[140:143], v[4:7]
	v_mfma_f32_16x16x32_bf16 v[8:11], v[74:77], v[144:147], v[8:11]
	v_mfma_f32_16x16x32_bf16 v[12:15], v[74:77], v[148:151], v[12:15]
	v_mfma_f32_16x16x32_bf16 v[16:19], v[118:121], v[136:139], v[16:19]
	v_mfma_f32_16x16x32_bf16 v[20:23], v[118:121], v[140:143], v[20:23]
	v_mfma_f32_16x16x32_bf16 v[24:27], v[118:121], v[144:147], v[24:27]
	v_mfma_f32_16x16x32_bf16 v[28:31], v[118:121], v[148:151], v[28:31]
	v_mfma_f32_16x16x32_bf16 v[74:77], v[122:125], v[136:139], v[32:35]
	v_mfma_f32_16x16x32_bf16 v[110:113], v[122:125], v[140:143], v[36:39]
	v_mfma_f32_16x16x32_bf16 v[114:117], v[122:125], v[144:147], v[40:43]
	v_mfma_f32_16x16x32_bf16 v[118:121], v[122:125], v[148:151], v[44:47]
	v_mfma_f32_16x16x32_bf16 v[122:125], v[132:135], v[136:139], v[48:51]
	v_mfma_f32_16x16x32_bf16 v[136:139], v[132:135], v[140:143], v[52:55]
	v_mfma_f32_16x16x32_bf16 v[140:143], v[132:135], v[144:147], v[56:59]
	v_mfma_f32_16x16x32_bf16 v[132:135], v[132:135], v[148:151], v[60:63]
	s_waitcnt lgkmcnt(0)
	v_mfma_f32_16x16x32_bf16 v[60:63], v[152:155], v[192:195], v[0:3]
	v_mfma_f32_16x16x32_bf16 v[56:59], v[152:155], v[196:199], v[4:7]
	v_mfma_f32_16x16x32_bf16 v[52:55], v[152:155], v[200:203], v[8:11]
	v_mfma_f32_16x16x32_bf16 v[48:51], v[152:155], v[204:207], v[12:15]
	v_mfma_f32_16x16x32_bf16 v[44:47], v[180:183], v[192:195], v[16:19]
	v_mfma_f32_16x16x32_bf16 v[40:43], v[180:183], v[196:199], v[20:23]
	v_mfma_f32_16x16x32_bf16 v[36:39], v[180:183], v[200:203], v[24:27]
	v_mfma_f32_16x16x32_bf16 v[32:35], v[180:183], v[204:207], v[28:31]
	v_mfma_f32_16x16x32_bf16 v[28:31], v[184:187], v[192:195], v[74:77]
	v_mfma_f32_16x16x32_bf16 v[24:27], v[184:187], v[196:199], v[110:113]
	v_mfma_f32_16x16x32_bf16 v[20:23], v[184:187], v[200:203], v[114:117]
	v_mfma_f32_16x16x32_bf16 v[16:19], v[184:187], v[204:207], v[118:121]
	v_mfma_f32_16x16x32_bf16 v[12:15], v[188:191], v[192:195], v[122:125]
	v_mfma_f32_16x16x32_bf16 v[8:11], v[188:191], v[196:199], v[136:139]
	v_mfma_f32_16x16x32_bf16 v[4:7], v[188:191], v[200:203], v[140:143]
	v_mfma_f32_16x16x32_bf16 v[0:3], v[188:191], v[204:207], v[132:135]
	s_setprio 0
	s_and_saveexec_b64 s[20:21], s[6:7]
	s_cbranch_execz .LBB0_4968
	v_lshl_add_u64 v[110:111], v[66:67], 0, s[18:19]
	v_add_co_u32_e32 v112, vcc, 0xfe9c000, v110
	v_lshlrev_b32_e32 v76, 16, v101
	s_nop 0
	v_addc_co_u32_e32 v113, vcc, 0, v111, vcc
	v_add_co_u32_e32 v74, vcc, 0xfe9e000, v110
	v_and_b32_e32 v77, 0xffff0000, v101
	s_nop 0
	v_addc_co_u32_e32 v75, vcc, 0, v111, vcc
	global_load_ushort v101, v[112:113], off offset:3072
	global_load_ushort v114, v[74:75], off offset:1024
	s_waitcnt vmcnt(0)
	v_lshlrev_b32_e32 v115, 16, v114
	v_lshlrev_b32_e32 v114, 16, v101
	v_pk_fma_f32 v[60:61], v[60:61], v[114:115], v[76:77]
	v_add_co_u32_e32 v76, vcc, s88, v110
	v_cvt_pk_bf16_f32 v101, v60, v61
	s_nop 0
	v_addc_co_u32_e32 v77, vcc, 0, v111, vcc
	v_add_co_u32_e32 v60, vcc, s93, v110
	v_lshlrev_b32_e32 v114, 16, v102
	s_nop 0
	v_addc_co_u32_e32 v61, vcc, 0, v111, vcc
	v_and_b32_e32 v115, 0xffff0000, v102
	global_load_ushort v102, v[76:77], off offset:3072
	global_load_ushort v110, v[60:61], off offset:1024
	s_waitcnt vmcnt(0)
	v_lshlrev_b32_e32 v111, 16, v110
	v_lshlrev_b32_e32 v110, 16, v102
	v_pk_fma_f32 v[62:63], v[62:63], v[110:111], v[114:115]
	s_nop 0
	v_cvt_pk_bf16_f32 v102, v62, v63
	v_lshlrev_b32_e32 v62, 16, v103
	v_and_b32_e32 v63, 0xffff0000, v103
	global_load_ushort v103, v[112:113], off offset:3104
	global_load_ushort v110, v[74:75], off offset:1056
	s_waitcnt vmcnt(0)
	v_lshlrev_b32_e32 v111, 16, v110
	v_lshlrev_b32_e32 v110, 16, v103
	v_pk_fma_f32 v[56:57], v[56:57], v[110:111], v[62:63]
	global_load_ushort v62, v[76:77], off offset:3104
	global_load_ushort v63, v[60:61], off offset:1056
	v_cvt_pk_bf16_f32 v103, v56, v57
	v_lshlrev_b32_e32 v56, 16, v96
	v_and_b32_e32 v57, 0xffff0000, v96
	s_waitcnt vmcnt(0)
	v_lshlrev_b32_e32 v62, 16, v62
	v_lshlrev_b32_e32 v63, 16, v63
	v_pk_fma_f32 v[56:57], v[58:59], v[62:63], v[56:57]
	global_load_ushort v58, v[112:113], off offset:3136
	global_load_ushort v59, v[74:75], off offset:1088
	v_cvt_pk_bf16_f32 v96, v56, v57
	v_lshlrev_b32_e32 v56, 16, v105
	v_and_b32_e32 v57, 0xffff0000, v105
	s_waitcnt vmcnt(0)
	v_lshlrev_b32_e32 v58, 16, v58
	v_lshlrev_b32_e32 v59, 16, v59
	v_pk_fma_f32 v[52:53], v[52:53], v[58:59], v[56:57]
	global_load_ushort v56, v[76:77], off offset:3136
	global_load_ushort v57, v[60:61], off offset:1088
	v_cvt_pk_bf16_f32 v105, v52, v53
	v_lshlrev_b32_e32 v52, 16, v95
	v_and_b32_e32 v53, 0xffff0000, v95
	s_waitcnt vmcnt(0)
	v_lshlrev_b32_e32 v56, 16, v56
	v_lshlrev_b32_e32 v57, 16, v57
	v_pk_fma_f32 v[52:53], v[54:55], v[56:57], v[52:53]
	global_load_ushort v54, v[112:113], off offset:3168
	global_load_ushort v55, v[74:75], off offset:1120
	v_cvt_pk_bf16_f32 v95, v52, v53
	v_lshlrev_b32_e32 v52, 16, v104
	v_and_b32_e32 v53, 0xffff0000, v104
	s_waitcnt vmcnt(0)
	v_lshlrev_b32_e32 v54, 16, v54
	v_lshlrev_b32_e32 v55, 16, v55
	v_pk_fma_f32 v[48:49], v[48:49], v[54:55], v[52:53]
	global_load_ushort v52, v[76:77], off offset:3168
	global_load_ushort v53, v[60:61], off offset:1120
	v_cvt_pk_bf16_f32 v104, v48, v49
	v_lshlrev_b32_e32 v48, 16, v109
	v_and_b32_e32 v49, 0xffff0000, v109
	s_waitcnt vmcnt(0)
	v_lshlrev_b32_e32 v52, 16, v52
	v_lshlrev_b32_e32 v53, 16, v53
	v_pk_fma_f32 v[48:49], v[50:51], v[52:53], v[48:49]
	s_nop 0
	v_cvt_pk_bf16_f32 v109, v48, v49

;     ...
;   for (int kt = 0; kt < nk; ++kt) {
;     asm volatile("s_waitcnt vmcnt(0)" ::: "memory");
;     __builtin_amdgcn_s_barrier();
;     if (kt + 1 < nk) stage(kt + 1, (kt + 1) & 1);
;     else if (chained && nbrow >= 0) {
;       const bfr* na = (nA ? nA : A) + (long)(nbrow + r0) * lda + cg;
;       const bfr* nb = (nBt ? nBt : Bt) + (long)(nbcol + r0) * ldb + cg;
; #pragma unroll
;       for (int i = 0; i < 4; ++i)
;         __builtin_amdgcn_global_load_lds((const unsigned*)(na + i * a32), (unsigned*)(smem + tid * 16 + i * 4096), 16, 0, 0);
; #pragma unroll
;       for (int i = 0; i < NF; ++i)
;         __builtin_amdgcn_global_load_lds((const unsigned*)(nb + i * b32), (unsigned*)(smem + 16384 + tid * 16 + i * 4096), 16, 0, 0);
;     }
;     const unsigned bo = (kt & 1) * 32768;
;     bf16x8 af[2][4], bfg[2][4];
;     if (NF == 4) {
;       asm volatile(
;           "ds_read_b128 %0, %16\n\tds_read_b128 %1, %16 offset:2048\n\tds_read_b128 %2, %16 offset:4096\n\tds_read_b128 %3, %16 offset:6144\n\t"
;           "ds_read_b128 %4, %17\n\tds_read_b128 %5, %17 offset:2048\n\tds_read_b128 %6, %17 offset:4096\n\tds_read_b128 %7, %17 offset:6144\n\t"
;           "ds_read_b128 %8, %18\n\tds_read_b128 %9, %18 offset:2048\n\tds_read_b128 %10, %18 offset:4096\n\tds_read_b128 %11, %18 offset:6144\n\t"
;           "ds_read_b128 %12, %19\n\tds_read_b128 %13, %19 offset:2048\n\tds_read_b128 %14, %19 offset:4096\n\tds_read_b128 %15, %19 offset:6144\n\t"
;           "s_waitcnt lgkmcnt(0)"
;           : "=&v"(af[0][0]), "=&v"(af[0][1]), "=&v"(af[0][2]), "=&v"(af[0][3]), "=&v"(bfg[0][0]), "=&v"(bfg[0][1]), "=&v"(bfg[0][2]), "=&v"(bfg[0][3]),
;             "=&v"(af[1][0]), "=&v"(af[1][1]), "=&v"(af[1][2]), "=&v"(af[1][3]), "=&v"(bfg[1][0]), "=&v"(bfg[1][1]), "=&v"(bfg[1][2]), "=&v"(bfg[1][3])
;           : "v"(arow + sw0 + bo), "v"(brw + sw0 + bo), "v"(arow + sw1 + bo), "v"(brw + sw1 + bo)
;           : "memory");
;     } else {
;       asm volatile(
;           "ds_read_b128 %0, %12\n\tds_read_b128 %1, %12 offset:2048\n\tds_read_b128 %2, %12 offset:4096\n\tds_read_b128 %3, %12 offset:6144\n\t"
;           "ds_read_b128 %4, %13\n\tds_read_b128 %5, %13 offset:2048\n\t"
;           "ds_read_b128 %6, %14\n\tds_read_b128 %7, %14 offset:2048\n\tds_read_b128 %8, %14 offset:4096\n\tds_read_b128 %9, %14 offset:6144\n\t"
.LBB0_5103:
	s_add_i32 s17, s16, 0x8000
	s_and_b32 s18, s17, 0x8000
	v_add_u32_e32 v65, s18, v76
	v_lshl_add_u64 v[78:79], v[66:67], 0, s[8:9]
	v_readfirstlane_b32 s18, v65
	v_add_u32_e32 v77, 0x1000, v65
	v_lshl_add_u64 v[80:81], v[78:79], 0, s[52:53]
	s_mov_b32 m0, s18
	v_readfirstlane_b32 s18, v77
	v_add_u32_e32 v77, 0x2000, v65
	s_waitcnt vmcnt(0)
	s_barrier
	global_load_lds_dwordx4 v[80:81], off
	v_lshl_add_u64 v[80:81], v[78:79], 0, s[54:55]
	s_mov_b32 m0, s18
	v_readfirstlane_b32 s18, v77
	v_add_u32_e32 v77, 0x3000, v65
	global_load_lds_dwordx4 v[80:81], off
	v_lshl_add_u64 v[80:81], v[78:79], 0, s[56:57]
	s_mov_b32 m0, s18
	v_readfirstlane_b32 s18, v77
	global_load_lds_dwordx4 v[80:81], off
	v_lshl_add_u64 v[78:79], v[78:79], 0, s[20:21]
	s_mov_b32 m0, s18
	v_add_u32_e32 v77, 0x4000, v65
	global_load_lds_dwordx4 v[78:79], off
	v_lshl_add_u64 v[78:79], v[68:69], 0, s[8:9]
	v_readfirstlane_b32 s18, v77
	v_add_u32_e32 v77, 0x5000, v65
	v_lshl_add_u64 v[80:81], v[78:79], 0, s[22:23]
	s_mov_b32 m0, s18
	v_readfirstlane_b32 s18, v77
	global_load_lds_dwordx4 v[80:81], off
	v_lshl_add_u64 v[80:81], v[78:79], 0, s[24:25]
	s_mov_b32 m0, s18
	s_mov_b64 s[18:19], 0x23e8480
	v_add_u32_e32 v77, 0x6000, v65
	global_load_lds_dwordx4 v[80:81], off
	v_lshl_add_u64 v[80:81], v[78:79], 0, s[18:19]
	v_readfirstlane_b32 s18, v77
	s_mov_b32 m0, s18
	s_mov_b64 s[18:19], 0x23f8480
	v_add_u32_e32 v65, 0x7000, v65
	v_lshl_add_u64 v[78:79], v[78:79], 0, s[18:19]
	v_readfirstlane_b32 s18, v65
	global_load_lds_dwordx4 v[80:81], off
	s_mov_b32 m0, s18
	s_and_b32 s16, s16, 0x8000
	global_load_lds_dwordx4 v[78:79], off
	v_add_u32_e32 v65, s16, v72
	v_add_u32_e32 v77, s16, v73
	v_add_u32_e32 v126, s16, v74
	v_add_u32_e32 v127, s16, v75
	ds_read_b128 v[78:81], v65
	ds_read_b128 v[82:85], v65 offset:2048
	ds_read_b128 v[86:89], v65 offset:4096
	ds_read_b128 v[90:93], v65 offset:6144
	ds_read_b128 v[94:97], v77
	ds_read_b128 v[98:101], v77 offset:2048
	ds_read_b128 v[102:105], v77 offset:4096
	ds_read_b128 v[106:109], v77 offset:6144
	ds_read_b128 v[110:113], v126
	ds_read_b128 v[114:117], v126 offset:2048
	ds_read_b128 v[118:121], v126 offset:4096
	ds_read_b128 v[122:125], v126 offset:6144
	ds_read_b128 v[132:135], v127
	ds_read_b128 v[136:139], v127 offset:2048
	ds_read_b128 v[140:143], v127 offset:4096
	ds_read_b128 v[144:147], v127 offset:6144
	s_waitcnt lgkmcnt(8)
	s_setprio 1
	v_mfma_f32_16x16x32_bf16 v[60:63], v[78:81], v[94:97], v[60:63]
	v_mfma_f32_16x16x32_bf16 v[56:59], v[78:81], v[98:101], v[56:59]
	v_mfma_f32_16x16x32_bf16 v[52:55], v[78:81], v[102:105], v[52:55]
	v_mfma_f32_16x16x32_bf16 v[48:51], v[78:81], v[106:109], v[48:51]
	v_mfma_f32_16x16x32_bf16 v[44:47], v[82:85], v[94:97], v[44:47]
	v_mfma_f32_16x16x32_bf16 v[40:43], v[82:85], v[98:101], v[40:43]
	v_mfma_f32_16x16x32_bf16 v[36:39], v[82:85], v[102:105], v[36:39]
	v_mfma_f32_16x16x32_bf16 v[32:35], v[82:85], v[106:109], v[32:35]
	v_mfma_f32_16x16x32_bf16 v[28:31], v[86:89], v[94:97], v[28:31]
	v_mfma_f32_16x16x32_bf16 v[24:27], v[86:89], v[98:101], v[24:27]
	v_mfma_f32_16x16x32_bf16 v[20:23], v[86:89], v[102:105], v[20:23]
	v_mfma_f32_16x16x32_bf16 v[16:19], v[86:89], v[106:109], v[16:19]
	v_mfma_f32_16x16x32_bf16 v[12:15], v[90:93], v[94:97], v[12:15]
	v_mfma_f32_16x16x32_bf16 v[8:11], v[90:93], v[98:101], v[8:11]
	v_mfma_f32_16x16x32_bf16 v[4:7], v[90:93], v[102:105], v[4:7]
	v_mfma_f32_16x16x32_bf16 v[0:3], v[90:93], v[106:109], v[0:3]
	s_waitcnt lgkmcnt(0)
	v_mfma_f32_16x16x32_bf16 v[60:63], v[110:113], v[132:135], v[60:63]
	v_mfma_f32_16x16x32_bf16 v[56:59], v[110:113], v[136:139], v[56:59]
	v_mfma_f32_16x16x32_bf16 v[52:55], v[110:113], v[140:143], v[52:55]
	v_mfma_f32_16x16x32_bf16 v[48:51], v[110:113], v[144:147], v[48:51]
	v_mfma_f32_16x16x32_bf16 v[44:47], v[114:117], v[132:135], v[44:47]
	v_mfma_f32_16x16x32_bf16 v[40:43], v[114:117], v[136:139], v[40:43]
	v_mfma_f32_16x16x32_bf16 v[36:39], v[114:117], v[140:143], v[36:39]
	v_mfma_f32_16x16x32_bf16 v[32:35], v[114:117], v[144:147], v[32:35]
	v_mfma_f32_16x16x32_bf16 v[28:31], v[118:121], v[132:135], v[28:31]
	v_mfma_f32_16x16x32_bf16 v[24:27], v[118:121], v[136:139], v[24:27]
	v_mfma_f32_16x16x32_bf16 v[20:23], v[118:121], v[140:143], v[20:23]
	v_mfma_f32_16x16x32_bf16 v[16:19], v[118:121], v[144:147], v[16:19]
	v_mfma_f32_16x16x32_bf16 v[12:15], v[122:125], v[132:135], v[12:15]
	v_mfma_f32_16x16x32_bf16 v[8:11], v[122:125], v[136:139], v[8:11]
	v_mfma_f32_16x16x32_bf16 v[4:7], v[122:125], v[140:143], v[4:7]
	v_mfma_f32_16x16x32_bf16 v[0:3], v[122:125], v[144:147], v[0:3]
	s_setprio 0
	s_add_u32 s8, s8, 0x80
	s_addc_u32 s9, s9, 0
	s_cmpk_eq_i32 s8, 0x780
	s_mov_b32 s16, s17
	s_cbranch_scc0 .LBB0_5103
	v_readlane_b32 s16, v249, 0
	v_readlane_b32 s18, v249, 2
	s_add_i32 s14, s14, s18
	v_readlane_b32 s17, v249, 1
	s_cmp_ge_i32 s14, s62
	s_mul_hi_i32 s16, s14, 0x77975b9
	s_cselect_b64 s[8:9], -1, 0
	s_lshr_b32 s17, s16, 31
	s_ashr_i32 s16, s16, 2
	s_add_i32 s16, s16, s17
	s_mul_i32 s17, s16, 0x89
	s_sub_i32 s17, s14, s17
	s_lshl_b32 s17, s17, 7
	s_cmp_lt_i32 s14, s62
	s_waitcnt vmcnt(0)
	s_cselect_b32 s17, s17, -1
	s_cmp_lt_i32 s17, 0
	s_mov_b64 s[20:21], 0x20000
	v_readlane_b32 s19, v249, 3
	s_barrier
	s_cbranch_scc1 .LBB0_5106
	v_add_u32_e32 v66, s17, v71
	v_lshl_add_u32 v68, s16, 7, v71
	v_ashrrev_i32_e32 v67, 31, v66
	v_ashrrev_i32_e32 v69, 31, v68
	v_lshlrev_b64 v[68:69], 11, v[68:69]
	v_lshlrev_b64 v[66:67], 11, v[66:67]
	v_lshl_add_u64 v[68:69], s[2:3], 0, v[68:69]
	v_lshl_add_u64 v[66:67], s[4:5], 0, v[66:67]
	v_mov_b32_e32 v65, v129
	v_readfirstlane_b32 s16, v76
	v_add_u32_e32 v77, 0x1000, v76
	v_lshl_add_u64 v[68:69], v[68:69], 0, v[64:65]
	v_lshl_add_u64 v[64:65], v[66:67], 0, v[64:65]
	s_mov_b32 m0, s16
	s_mov_b64 s[18:19], 0x10000
	v_readfirstlane_b32 s16, v77
	v_add_u32_e32 v77, 0x2000, v76
	global_load_lds_dwordx4 v[64:65], off
	v_lshl_add_u64 v[66:67], v[64:65], 0, s[18:19]
	s_mov_b32 m0, s16
	v_readfirstlane_b32 s16, v77
	global_load_lds_dwordx4 v[66:67], off
	v_lshl_add_u64 v[66:67], v[64:65], 0, s[20:21]
	s_mov_b32 m0, s16
	v_add_u32_e32 v71, 0x4000, v76
	global_load_lds_dwordx4 v[66:67], off
	v_add_u32_e32 v66, 0x3000, v76
	s_mov_b64 s[22:23], 0x30000
	v_readfirstlane_b32 s16, v66
	v_lshl_add_u64 v[64:65], v[64:65], 0, s[22:23]
	s_mov_b32 m0, s16
	v_readfirstlane_b32 s16, v71
	v_add_u32_e32 v66, 0x5000, v76
	global_load_lds_dwordx4 v[64:65], off
	s_mov_b32 m0, s16
	v_readfirstlane_b32 s16, v66
	v_add_u32_e32 v66, 0x6000, v76
	global_load_lds_dwordx4 v[68:69], off
	v_lshl_add_u64 v[64:65], v[68:69], 0, s[18:19]
	s_mov_b32 m0, s16
	v_readfirstlane_b32 s16, v66
	v_add_u32_e32 v66, 0x7000, v76
	global_load_lds_dwordx4 v[64:65], off
	v_lshl_add_u64 v[64:65], v[68:69], 0, s[20:21]
	s_mov_b32 m0, s16
	v_readfirstlane_b32 s16, v66
	global_load_lds_dwordx4 v[64:65], off
	v_lshl_add_u64 v[64:65], v[68:69], 0, s[22:23]
	s_mov_b32 m0, s16
	s_nop 0
	global_load_lds_dwordx4 v[64:65], off
;     ...
;     const unsigned bo = (kt & 1) * 32768;
;     bf16x8 af[2][4], bfg[2][4];
;     if (NF == 4) {
;       asm volatile(
;           "ds_read_b128 %0, %16\n\tds_read_b128 %1, %16 offset:2048\n\tds_read_b128 %2, %16 offset:4096\n\tds_read_b128 %3, %16 offset:6144\n\t"
;           "ds_read_b128 %4, %17\n\tds_read_b128 %5, %17 offset:2048\n\tds_read_b128 %6, %17 offset:4096\n\tds_read_b128 %7, %17 offset:6144\n\t"
;           "ds_read_b128 %8, %18\n\tds_read_b128 %9, %18 offset:2048\n\tds_read_b128 %10, %18 offset:4096\n\tds_read_b128 %11, %18 offset:6144\n\t"
;           "ds_read_b128 %12, %19\n\tds_read_b128 %13, %19 offset:2048\n\tds_read_b128 %14, %19 offset:4096\n\tds_read_b128 %15, %19 offset:6144\n\t"
;           "s_waitcnt lgkmcnt(0)"
;           : "=&v"(af[0][0]), "=&v"(af[0][1]), "=&v"(af[0][2]), "=&v"(af[0][3]), "=&v"(bfg[0][0]), "=&v"(bfg[0][1]), "=&v"(bfg[0][2]), "=&v"(bfg[0][3]),
;             "=&v"(af[1][0]), "=&v"(af[1][1]), "=&v"(af[1][2]), "=&v"(af[1][3]), "=&v"(bfg[1][0]), "=&v"(bfg[1][1]), "=&v"(bfg[1][2]), "=&v"(bfg[1][3])
;           : "v"(arow + sw0 + bo), "v"(brw + sw0 + bo), "v"(arow + sw1 + bo), "v"(brw + sw1 + bo)
;           : "memory");
;     } else {
;       asm volatile(
;           "ds_read_b128 %0, %12\n\tds_read_b128 %1, %12 offset:2048\n\tds_read_b128 %2, %12 offset:4096\n\tds_read_b128 %3, %12 offset:6144\n\t"
;           "ds_read_b128 %4, %13\n\tds_read_b128 %5, %13 offset:2048\n\t"
;           "ds_read_b128 %6, %14\n\tds_read_b128 %7, %14 offset:2048\n\tds_read_b128 %8, %14 offset:4096\n\tds_read_b128 %9, %14 offset:6144\n\t"
;           "ds_read_b128 %10, %15\n\tds_read_b128 %11, %15 offset:2048\n\t"
;           "s_waitcnt lgkmcnt(0)"
;           : "=&v"(af[0][0]), "=&v"(af[0][1]), "=&v"(af[0][2]), "=&v"(af[0][3]), "=&v"(bfg[0][0]), "=&v"(bfg[0][1]),
;             "=&v"(af[1][0]), "=&v"(af[1][1]), "=&v"(af[1][2]), "=&v"(af[1][3]), "=&v"(bfg[1][0]), "=&v"(bfg[1][1])
;           : "v"(arow + sw0 + bo), "v"(brw + sw0 + bo), "v"(arow + sw1 + bo), "v"(brw + sw1 + bo)
;           : "memory");
;     }
;     __builtin_amdgcn_s_setprio(1);
; #pragma unroll
;     for (int ks = 0; ks < 2; ++ks)
; #pragma unroll
;       for (int m = 0; m < 4; ++m)
; #pragma unroll
;         for (int n = 0; n < NF; ++n) acc[m][n] = MFMA16(af[ks][m], bfg[ks][n], acc[m][n]);
;     __builtin_amdgcn_s_setprio(0);
;   }
.LBB0_5106:
	v_add_u32_e32 v69, 0x8000, v72
	v_add_u32_e32 v71, 0x8000, v73
	v_add_u32_e32 v128, 0x8000, v74
	v_add_u32_e32 v136, 0x8000, v75
	ds_read_b128 v[64:67], v69
	ds_read_b128 v[72:75], v69 offset:2048
	ds_read_b128 v[76:79], v69 offset:4096
	ds_read_b128 v[80:83], v69 offset:6144
	ds_read_b128 v[84:87], v71
	ds_read_b128 v[88:91], v71 offset:2048
	ds_read_b128 v[92:95], v71 offset:4096
	ds_read_b128 v[96:99], v71 offset:6144
	ds_read_b128 v[100:103], v128
	ds_read_b128 v[104:107], v128 offset:2048
	ds_read_b128 v[108:111], v128 offset:4096
	ds_read_b128 v[112:115], v128 offset:6144
	ds_read_b128 v[116:119], v136
	ds_read_b128 v[120:123], v136 offset:2048
	ds_read_b128 v[124:127], v136 offset:4096
	ds_read_b128 v[132:135], v136 offset:6144
	s_waitcnt lgkmcnt(0)
	s_and_b32 s16, s15, 64
	v_and_b32_e32 v68, 15, v70
	s_setprio 1
	v_mfma_f32_16x16x32_bf16 v[60:63], v[64:67], v[84:87], v[60:63]
	v_mfma_f32_16x16x32_bf16 v[56:59], v[64:67], v[88:91], v[56:59]
	v_mfma_f32_16x16x32_bf16 v[52:55], v[64:67], v[92:95], v[52:55]
	v_mfma_f32_16x16x32_bf16 v[48:51], v[64:67], v[96:99], v[48:51]
	v_mfma_f32_16x16x32_bf16 v[44:47], v[72:75], v[84:87], v[44:47]
	v_mfma_f32_16x16x32_bf16 v[40:43], v[72:75], v[88:91], v[40:43]
	v_mfma_f32_16x16x32_bf16 v[36:39], v[72:75], v[92:95], v[36:39]
	v_mfma_f32_16x16x32_bf16 v[32:35], v[72:75], v[96:99], v[32:35]
	v_mfma_f32_16x16x32_bf16 v[28:31], v[76:79], v[84:87], v[28:31]
	v_mfma_f32_16x16x32_bf16 v[24:27], v[76:79], v[88:91], v[24:27]
	v_mfma_f32_16x16x32_bf16 v[20:23], v[76:79], v[92:95], v[20:23]
	v_mfma_f32_16x16x32_bf16 v[16:19], v[76:79], v[96:99], v[16:19]
	v_mfma_f32_16x16x32_bf16 v[12:15], v[80:83], v[84:87], v[12:15]
	v_mfma_f32_16x16x32_bf16 v[8:11], v[80:83], v[88:91], v[8:11]
	v_mfma_f32_16x16x32_bf16 v[4:7], v[80:83], v[92:95], v[4:7]
	v_mfma_f32_16x16x32_bf16 v[0:3], v[80:83], v[96:99], v[0:3]
	v_mfma_f32_16x16x32_bf16 v[60:63], v[100:103], v[116:119], v[60:63]
	v_mfma_f32_16x16x32_bf16 v[56:59], v[100:103], v[120:123], v[56:59]
	v_mfma_f32_16x16x32_bf16 v[52:55], v[100:103], v[124:127], v[52:55]
	v_mfma_f32_16x16x32_bf16 v[48:51], v[100:103], v[132:135], v[48:51]
	v_mfma_f32_16x16x32_bf16 v[44:47], v[104:107], v[116:119], v[44:47]
	v_mfma_f32_16x16x32_bf16 v[40:43], v[104:107], v[120:123], v[40:43]
	v_mfma_f32_16x16x32_bf16 v[36:39], v[104:107], v[124:127], v[36:39]
	v_mfma_f32_16x16x32_bf16 v[32:35], v[104:107], v[132:135], v[32:35]
	v_mfma_f32_16x16x32_bf16 v[28:31], v[108:111], v[116:119], v[28:31]
	v_mfma_f32_16x16x32_bf16 v[24:27], v[108:111], v[120:123], v[24:27]
	v_mfma_f32_16x16x32_bf16 v[20:23], v[108:111], v[124:127], v[20:23]
	v_mfma_f32_16x16x32_bf16 v[16:19], v[108:111], v[132:135], v[16:19]
	v_mfma_f32_16x16x32_bf16 v[12:15], v[112:115], v[116:119], v[12:15]
	v_mfma_f32_16x16x32_bf16 v[8:11], v[112:115], v[120:123], v[8:11]
	v_mfma_f32_16x16x32_bf16 v[4:7], v[112:115], v[124:127], v[4:7]
	v_mfma_f32_16x16x32_bf16 v[0:3], v[112:115], v[132:135], v[0:3]
	s_setprio 0
	v_lshrrev_b32_e32 v64, 2, v70
	s_ashr_i32 s15, s15, 1
	v_and_or_b32 v64, v64, 12, s11
	s_ashr_i32 s11, s10, 31
	s_andn2_b32 s15, s15, 63
	s_lshl_b64 s[10:11], s[10:11], 2
	s_add_u32 s10, s12, s10
	v_add_u32_e32 v64, s15, v64
	s_addc_u32 s11, s13, s11
	s_lshl_b32 s15, s16, 2
	s_add_u32 s10, s10, s15
	s_addc_u32 s11, s11, 0
	v_lshlrev_b32_e32 v128, 2, v68
	v_lshl_add_u64 v[66:67], s[10:11], 0, v[128:129]
	s_mov_b64 s[24:25], 0x1000
	s_mov_b64 s[26:27], 0x2000
	s_mov_b64 s[28:29], 0x3000
	v_mov_b32_e32 v128, v64
	v_cmp_gt_i32_e64 s[16:17], s79, v128
	v_lshlrev_b64 v[180:181], 12, v[128:129]
	v_lshl_add_u64 v[180:181], v[66:67], 0, v[180:181]
	v_lshl_add_u64 v[182:183], v[180:181], 0, s[24:25]
	v_lshl_add_u64 v[184:185], v[180:181], 0, s[26:27]
	v_lshl_add_u64 v[186:187], v[180:181], 0, s[28:29]
	v_or_b32_e32 v128, 16, v64
	v_cmp_gt_i32_e64 s[18:19], s79, v128
	v_lshlrev_b64 v[188:189], 12, v[128:129]
	v_lshl_add_u64 v[188:189], v[66:67], 0, v[188:189]
	v_lshl_add_u64 v[190:191], v[188:189], 0, s[24:25]
	v_lshl_add_u64 v[192:193], v[188:189], 0, s[26:27]
	v_lshl_add_u64 v[194:195], v[188:189], 0, s[28:29]
	v_or_b32_e32 v128, 32, v64
	v_cmp_gt_i32_e64 s[20:21], s79, v128
	v_lshlrev_b64 v[196:197], 12, v[128:129]
	v_lshl_add_u64 v[196:197], v[66:67], 0, v[196:197]
	v_lshl_add_u64 v[198:199], v[196:197], 0, s[24:25]
	v_lshl_add_u64 v[200:201], v[196:197], 0, s[26:27]
	v_lshl_add_u64 v[202:203], v[196:197], 0, s[28:29]
	v_or_b32_e32 v128, 48, v64
	v_cmp_gt_i32_e64 s[22:23], s79, v128
	v_lshlrev_b64 v[204:205], 12, v[128:129]
	v_lshl_add_u64 v[204:205], v[66:67], 0, v[204:205]
	v_lshl_add_u64 v[206:207], v[204:205], 0, s[24:25]
	v_lshl_add_u64 v[208:209], v[204:205], 0, s[26:27]
	v_lshl_add_u64 v[210:211], v[204:205], 0, s[28:29]
	s_mov_b64 exec, s[16:17]
	global_load_dword v68, v[180:181], off
	global_load_dword v69, v[180:181], off offset:64
	global_load_dword v70, v[180:181], off offset:128
	global_load_dword v71, v[180:181], off offset:192
	global_load_dword v72, v[182:183], off
	global_load_dword v73, v[182:183], off offset:64
	global_load_dword v74, v[182:183], off offset:128
	global_load_dword v75, v[182:183], off offset:192
	global_load_dword v76, v[184:185], off
	global_load_dword v77, v[184:185], off offset:64
	global_load_dword v78, v[184:185], off offset:128
	global_load_dword v79, v[184:185], off offset:192
	global_load_dword v80, v[186:187], off
	global_load_dword v81, v[186:187], off offset:64
	global_load_dword v82, v[186:187], off offset:128
	global_load_dword v83, v[186:187], off offset:192
	s_mov_b64 exec, s[18:19]
	global_load_dword v84, v[188:189], off
	global_load_dword v85, v[188:189], off offset:64
; template <int NF>
; DI void out_tile(const Params& p, int layer, int brow, int bcol, bool& first, bool hasNext, int nbrow, int nbcol) {
;     ...
; #pragma unroll
;   for (int m = 0; m < 4; ++m)
; #pragma unroll
;     for (int j = 0; j < 4; ++j) {
;       int row = brow + wr * 64 + m * 16 + fq * 4 + j;
;       if (row < ROWS) {
; #pragma unroll
;         for (int n = 0; n < NF; ++n) xres[(long)row * 1024 + bcol + wc * (NF * 16) + n * 16 + fr] += acc[m][n][j];
;       }
	global_load_dword v86, v[188:189], off offset:128
	global_load_dword v87, v[188:189], off offset:192
	global_load_dword v88, v[190:191], off
	global_load_dword v89, v[190:191], off offset:64
	global_load_dword v90, v[190:191], off offset:128
	global_load_dword v91, v[190:191], off offset:192
	global_load_dword v92, v[192:193], off
	global_load_dword v93, v[192:193], off offset:64
	global_load_dword v94, v[192:193], off offset:128
	global_load_dword v95, v[192:193], off offset:192
	global_load_dword v96, v[194:195], off
	global_load_dword v97, v[194:195], off offset:64
	global_load_dword v98, v[194:195], off offset:128
	global_load_dword v99, v[194:195], off offset:192
	s_mov_b64 exec, s[20:21]
	global_load_dword v100, v[196:197], off
	global_load_dword v101, v[196:197], off offset:64
	global_load_dword v102, v[196:197], off offset:128
	global_load_dword v103, v[196:197], off offset:192
	global_load_dword v104, v[198:199], off
	global_load_dword v105, v[198:199], off offset:64
	global_load_dword v106, v[198:199], off offset:128
	global_load_dword v107, v[198:199], off offset:192
	global_load_dword v108, v[200:201], off
	global_load_dword v109, v[200:201], off offset:64
	global_load_dword v110, v[200:201], off offset:128
	global_load_dword v111, v[200:201], off offset:192
	global_load_dword v112, v[202:203], off
	global_load_dword v113, v[202:203], off offset:64
	global_load_dword v114, v[202:203], off offset:128
	global_load_dword v115, v[202:203], off offset:192
	s_mov_b64 exec, s[22:23]
	global_load_dword v116, v[204:205], off
	global_load_dword v117, v[204:205], off offset:64
	global_load_dword v118, v[204:205], off offset:128
	global_load_dword v119, v[204:205], off offset:192
	global_load_dword v120, v[206:207], off
	global_load_dword v121, v[206:207], off offset:64
	global_load_dword v122, v[206:207], off offset:128
	global_load_dword v123, v[206:207], off offset:192
	global_load_dword v124, v[208:209], off
	global_load_dword v125, v[208:209], off offset:64
	global_load_dword v126, v[208:209], off offset:128
	global_load_dword v127, v[208:209], off offset:192
	global_load_dword v140, v[210:211], off
	global_load_dword v141, v[210:211], off offset:64
	global_load_dword v142, v[210:211], off offset:128
	global_load_dword v143, v[210:211], off offset:192
	s_mov_b64 exec, s[16:17]
	s_waitcnt vmcnt(63)
	v_add_f32_e32 v60, v60, v68
	global_store_dword v[180:181], v60, off
	s_waitcnt vmcnt(63)
	v_add_f32_e32 v56, v56, v69
	global_store_dword v[180:181], v56, off offset:64
	s_waitcnt vmcnt(63)
	v_add_f32_e32 v52, v52, v70
	global_store_dword v[180:181], v52, off offset:128
	s_waitcnt vmcnt(63)
	v_add_f32_e32 v48, v48, v71
	global_store_dword v[180:181], v48, off offset:192
	s_waitcnt vmcnt(63)
	v_add_f32_e32 v61, v61, v72
	global_store_dword v[182:183], v61, off
	s_waitcnt vmcnt(63)
	v_add_f32_e32 v57, v57, v73
	global_store_dword v[182:183], v57, off offset:64
	s_waitcnt vmcnt(63)
	v_add_f32_e32 v53, v53, v74
	global_store_dword v[182:183], v53, off offset:128
	s_waitcnt vmcnt(63)
	v_add_f32_e32 v49, v49, v75
	global_store_dword v[182:183], v49, off offset:192
	s_waitcnt vmcnt(63)
	v_add_f32_e32 v62, v62, v76
	global_store_dword v[184:185], v62, off
	s_waitcnt vmcnt(63)
	v_add_f32_e32 v58, v58, v77
	global_store_dword v[184:185], v58, off offset:64
	s_waitcnt vmcnt(63)
	v_add_f32_e32 v54, v54, v78
	global_store_dword v[184:185], v54, off offset:128
	s_waitcnt vmcnt(63)
	v_add_f32_e32 v50, v50, v79
	global_store_dword v[184:185], v50, off offset:192
	s_waitcnt vmcnt(63)
	v_add_f32_e32 v63, v63, v80
	global_store_dword v[186:187], v63, off
	s_waitcnt vmcnt(63)
	v_add_f32_e32 v59, v59, v81
	global_store_dword v[186:187], v59, off offset:64
	s_waitcnt vmcnt(63)
	v_add_f32_e32 v55, v55, v82
	global_store_dword v[186:187], v55, off offset:128
	s_waitcnt vmcnt(63)
	v_add_f32_e32 v51, v51, v83
	global_store_dword v[186:187], v51, off offset:192
	s_mov_b64 exec, s[18:19]
	s_waitcnt vmcnt(63)
	v_add_f32_e32 v44, v44, v84
	global_store_dword v[188:189], v44, off
	s_waitcnt vmcnt(63)
	v_add_f32_e32 v40, v40, v85
	global_store_dword v[188:189], v40, off offset:64
	s_waitcnt vmcnt(63)
	v_add_f32_e32 v36, v36, v86
	global_store_dword v[188:189], v36, off offset:128
	s_waitcnt vmcnt(63)
	v_add_f32_e32 v32, v32, v87
	global_store_dword v[188:189], v32, off offset:192
	s_waitcnt vmcnt(63)
	v_add_f32_e32 v45, v45, v88
	global_store_dword v[190:191], v45, off
	s_waitcnt vmcnt(63)
; template <int NF>
; DI void out_tile(const Params& p, int layer, int brow, int bcol, bool& first, bool hasNext, int nbrow, int nbcol) {
;     ...
; #pragma unroll
;   for (int m = 0; m < 4; ++m)
; #pragma unroll
;     for (int j = 0; j < 4; ++j) {
;       int row = brow + wr * 64 + m * 16 + fq * 4 + j;
;       if (row < ROWS) {
; #pragma unroll
;         for (int n = 0; n < NF; ++n) xres[(long)row * 1024 + bcol + wc * (NF * 16) + n * 16 + fr] += acc[m][n][j];
;       }
	v_add_f32_e32 v41, v41, v89
	global_store_dword v[190:191], v41, off offset:64
	s_waitcnt vmcnt(63)
	v_add_f32_e32 v37, v37, v90
	global_store_dword v[190:191], v37, off offset:128
	s_waitcnt vmcnt(63)
	v_add_f32_e32 v33, v33, v91
	global_store_dword v[190:191], v33, off offset:192
	s_waitcnt vmcnt(63)
	v_add_f32_e32 v46, v46, v92
	global_store_dword v[192:193], v46, off
	s_waitcnt vmcnt(63)
	v_add_f32_e32 v42, v42, v93
	global_store_dword v[192:193], v42, off offset:64
	s_waitcnt vmcnt(63)
	v_add_f32_e32 v38, v38, v94
	global_store_dword v[192:193], v38, off offset:128
	s_waitcnt vmcnt(63)
	v_add_f32_e32 v34, v34, v95
	global_store_dword v[192:193], v34, off offset:192
	s_waitcnt vmcnt(63)
	v_add_f32_e32 v47, v47, v96
	global_store_dword v[194:195], v47, off
	s_waitcnt vmcnt(63)
	v_add_f32_e32 v43, v43, v97
	global_store_dword v[194:195], v43, off offset:64
	s_waitcnt vmcnt(63)
	v_add_f32_e32 v39, v39, v98
	global_store_dword v[194:195], v39, off offset:128
	s_waitcnt vmcnt(63)
	v_add_f32_e32 v35, v35, v99
	global_store_dword v[194:195], v35, off offset:192
	s_mov_b64 exec, s[20:21]
	s_waitcnt vmcnt(63)
	v_add_f32_e32 v28, v28, v100
	global_store_dword v[196:197], v28, off
	s_waitcnt vmcnt(63)
	v_add_f32_e32 v24, v24, v101
	global_store_dword v[196:197], v24, off offset:64
	s_waitcnt vmcnt(63)
	v_add_f32_e32 v20, v20, v102
	global_store_dword v[196:197], v20, off offset:128
	s_waitcnt vmcnt(63)
	v_add_f32_e32 v16, v16, v103
	global_store_dword v[196:197], v16, off offset:192
	s_waitcnt vmcnt(63)
	v_add_f32_e32 v29, v29, v104
	global_store_dword v[198:199], v29, off
	s_waitcnt vmcnt(63)
	v_add_f32_e32 v25, v25, v105
	global_store_dword v[198:199], v25, off offset:64
	s_waitcnt vmcnt(63)
	v_add_f32_e32 v21, v21, v106
	global_store_dword v[198:199], v21, off offset:128
	s_waitcnt vmcnt(63)
	v_add_f32_e32 v17, v17, v107
	global_store_dword v[198:199], v17, off offset:192
	s_waitcnt vmcnt(63)
	v_add_f32_e32 v30, v30, v108
	global_store_dword v[200:201], v30, off
	s_waitcnt vmcnt(63)
	v_add_f32_e32 v26, v26, v109
	global_store_dword v[200:201], v26, off offset:64
	s_waitcnt vmcnt(63)
	v_add_f32_e32 v22, v22, v110
	global_store_dword v[200:201], v22, off offset:128
	s_waitcnt vmcnt(63)
	v_add_f32_e32 v18, v18, v111
	global_store_dword v[200:201], v18, off offset:192
	s_waitcnt vmcnt(63)
	v_add_f32_e32 v31, v31, v112
	global_store_dword v[202:203], v31, off
	s_waitcnt vmcnt(63)
	v_add_f32_e32 v27, v27, v113
	global_store_dword v[202:203], v27, off offset:64
	s_waitcnt vmcnt(63)
	v_add_f32_e32 v23, v23, v114
	global_store_dword v[202:203], v23, off offset:128
	s_waitcnt vmcnt(63)
	v_add_f32_e32 v19, v19, v115
	global_store_dword v[202:203], v19, off offset:192
	s_mov_b64 exec, s[22:23]
	s_waitcnt vmcnt(63)
	v_add_f32_e32 v12, v12, v116
	global_store_dword v[204:205], v12, off
	s_waitcnt vmcnt(63)
	v_add_f32_e32 v8, v8, v117
	global_store_dword v[204:205], v8, off offset:64
	s_waitcnt vmcnt(63)
	v_add_f32_e32 v4, v4, v118
	global_store_dword v[204:205], v4, off offset:128
	s_waitcnt vmcnt(63)
	v_add_f32_e32 v0, v0, v119
	global_store_dword v[204:205], v0, off offset:192
	s_waitcnt vmcnt(63)
	v_add_f32_e32 v13, v13, v120
	global_store_dword v[206:207], v13, off
	s_waitcnt vmcnt(63)
	v_add_f32_e32 v9, v9, v121
	global_store_dword v[206:207], v9, off offset:64
	s_waitcnt vmcnt(63)
	v_add_f32_e32 v5, v5, v122
	global_store_dword v[206:207], v5, off offset:128
	s_waitcnt vmcnt(63)
	v_add_f32_e32 v1, v1, v123
	global_store_dword v[206:207], v1, off offset:192
	s_waitcnt vmcnt(63)
	v_add_f32_e32 v14, v14, v124
	global_store_dword v[208:209], v14, off
	s_waitcnt vmcnt(63)
	v_add_f32_e32 v10, v10, v125
	global_store_dword v[208:209], v10, off offset:64
	s_waitcnt vmcnt(63)
	v_add_f32_e32 v6, v6, v126
	global_store_dword v[208:209], v6, off offset:128
	s_waitcnt vmcnt(63)
	v_add_f32_e32 v2, v2, v127
	global_store_dword v[208:209], v2, off offset:192
	s_waitcnt vmcnt(63)
	v_add_f32_e32 v15, v15, v140
	global_store_dword v[210:211], v15, off
	s_waitcnt vmcnt(63)
	v_add_f32_e32 v11, v11, v141
	global_store_dword v[210:211], v11, off offset:64
	s_waitcnt vmcnt(63)
	v_add_f32_e32 v7, v7, v142
	global_store_dword v[210:211], v7, off offset:128
	s_waitcnt vmcnt(63)
	v_add_f32_e32 v3, v3, v143
	global_store_dword v[210:211], v3, off offset:192
	s_mov_b64 exec, -1
	s_mov_b64 s[10:11], -1
	s_branch .LBB0_5097
